# FF1 epilogues by hand: the fq lanes trade halves (ds_permute) so each lane stores 8 consecutive bf16; H is written as 64-byte row pieces instead of 32-byte fragments
# speedup vs baseline: 1.0233x; 1.0191x over previous
.LBB0_1396:
	ds_read_b128 v[150:153], v145
	ds_read_b128 v[154:157], v145 offset:1024
	ds_read_b128 v[158:161], v145 offset:2048
	ds_read_b128 v[162:165], v145 offset:3072
	s_add_u32 s33, s34, 0xfffc0080
	s_addc_u32 s36, s35, -1
	s_cmp_eq_u32 s71, 12
	s_cselect_b32 s41, s25, s36
	s_cselect_b32 s40, s67, s33
	s_cselect_b32 s37, s23, s70
	s_cselect_b32 s36, s68, s69
	v_lshl_add_u64 v[206:207], s[34:35], 0, v[136:137]
	s_add_i32 m0, s54, 0xc000
	ds_read_b128 v[166:169], v146
	ds_read_b128 v[178:181], v146 offset:1024
	ds_read_b128 v[182:185], v146 offset:2048
	ds_read_b128 v[186:189], v146 offset:3072
	ds_read_b128 v[190:193], v146 offset:4096
	ds_read_b128 v[194:197], v146 offset:5120
	ds_read_b128 v[198:201], v146 offset:6144
	ds_read_b128 v[202:205], v146 offset:7168
	global_load_lds_dwordx4 v[206:207], off
	v_lshl_add_u64 v[206:207], s[34:35], 0, v[134:135]
	s_add_i32 m0, s54, 0xe000
	s_nop 0
	global_load_lds_dwordx4 v[206:207], off
	s_waitcnt lgkmcnt(8)
	s_barrier
	s_waitcnt lgkmcnt(0)
	s_setprio 1
	s_waitcnt lgkmcnt(0)
	v_mfma_f32_16x16x32_bf16 v[124:127], v[150:153], v[166:169], v[124:127]
	v_mfma_f32_16x16x32_bf16 v[120:123], v[158:161], v[166:169], v[120:123]
	v_mfma_f32_16x16x32_bf16 v[116:119], v[150:153], v[182:185], v[116:119]
	v_mfma_f32_16x16x32_bf16 v[112:115], v[158:161], v[182:185], v[112:115]
	v_mfma_f32_16x16x32_bf16 v[108:111], v[150:153], v[190:193], v[108:111]
	v_mfma_f32_16x16x32_bf16 v[104:107], v[158:161], v[190:193], v[104:107]
	v_mfma_f32_16x16x32_bf16 v[100:103], v[150:153], v[198:201], v[100:103]
	v_mfma_f32_16x16x32_bf16 v[96:99], v[158:161], v[198:201], v[96:99]
	v_mfma_f32_16x16x32_bf16 v[124:127], v[154:157], v[178:181], v[124:127]
	v_mfma_f32_16x16x32_bf16 v[120:123], v[162:165], v[178:181], v[120:123]
	v_mfma_f32_16x16x32_bf16 v[116:119], v[154:157], v[186:189], v[116:119]
	v_mfma_f32_16x16x32_bf16 v[112:115], v[162:165], v[186:189], v[112:115]
	v_mfma_f32_16x16x32_bf16 v[108:111], v[154:157], v[194:197], v[108:111]
	v_mfma_f32_16x16x32_bf16 v[104:107], v[162:165], v[194:197], v[104:107]
	v_mfma_f32_16x16x32_bf16 v[100:103], v[154:157], v[202:205], v[100:103]
	v_mfma_f32_16x16x32_bf16 v[96:99], v[162:165], v[202:205], v[96:99]
	s_setprio 0
	s_barrier
	s_add_i32 s33, s65, s53
	v_lshl_add_u64 v[222:223], s[36:37], 0, v[130:131]
	s_mov_b32 m0, s33
	ds_read_b128 v[206:209], v147
	ds_read_b128 v[210:213], v147 offset:1024
	ds_read_b128 v[214:217], v147 offset:2048
	ds_read_b128 v[218:221], v147 offset:3072
	global_load_lds_dwordx4 v[222:223], off
	v_lshl_add_u64 v[224:225], s[36:37], 0, v[128:129]
	s_add_i32 m0, s33, 0x2000
	s_nop 0
	global_load_lds_dwordx4 v[224:225], off
	s_barrier
	s_waitcnt lgkmcnt(0)
	s_setprio 1
	s_waitcnt lgkmcnt(0)
	v_mfma_f32_16x16x32_bf16 v[92:95], v[206:209], v[166:169], v[92:95]
	v_mfma_f32_16x16x32_bf16 v[88:91], v[214:217], v[166:169], v[88:91]
	v_mfma_f32_16x16x32_bf16 v[84:87], v[206:209], v[182:185], v[84:87]
	v_mfma_f32_16x16x32_bf16 v[80:83], v[214:217], v[182:185], v[80:83]
	v_mfma_f32_16x16x32_bf16 v[76:79], v[206:209], v[190:193], v[76:79]
	v_mfma_f32_16x16x32_bf16 v[72:75], v[214:217], v[190:193], v[72:75]
	v_mfma_f32_16x16x32_bf16 v[68:71], v[206:209], v[198:201], v[68:71]
	v_mfma_f32_16x16x32_bf16 v[64:67], v[214:217], v[198:201], v[64:67]
	v_mfma_f32_16x16x32_bf16 v[92:95], v[210:213], v[178:181], v[92:95]
	v_mfma_f32_16x16x32_bf16 v[88:91], v[218:221], v[178:181], v[88:91]
	v_mfma_f32_16x16x32_bf16 v[84:87], v[210:213], v[186:189], v[84:87]
	v_mfma_f32_16x16x32_bf16 v[80:83], v[218:221], v[186:189], v[80:83]
	v_mfma_f32_16x16x32_bf16 v[76:79], v[210:213], v[194:197], v[76:79]
	v_mfma_f32_16x16x32_bf16 v[72:75], v[218:221], v[194:197], v[72:75]
	v_mfma_f32_16x16x32_bf16 v[68:71], v[210:213], v[202:205], v[68:71]
	v_mfma_f32_16x16x32_bf16 v[64:67], v[218:221], v[202:205], v[64:67]
	s_setprio 0
	s_mov_b32 m0, s54
	v_lshl_add_u64 v[226:227], s[40:41], 0, v[130:131]
	s_barrier
	ds_read_b128 v[166:169], v146 offset:16384
	ds_read_b128 v[178:181], v146 offset:17408
	ds_read_b128 v[182:185], v146 offset:18432
	ds_read_b128 v[186:189], v146 offset:19456
	ds_read_b128 v[190:193], v146 offset:20480
	ds_read_b128 v[194:197], v146 offset:21504
	ds_read_b128 v[198:201], v146 offset:22528
	ds_read_b128 v[202:205], v146 offset:23552
	global_load_lds_dwordx4 v[226:227], off
	v_lshl_add_u64 v[228:229], s[40:41], 0, v[128:129]
	s_mov_b32 m0, s55
	s_nop 0
	global_load_lds_dwordx4 v[228:229], off
	s_barrier
	s_waitcnt lgkmcnt(0)
	s_setprio 1
	s_waitcnt lgkmcnt(0)
	v_mfma_f32_16x16x32_bf16 v[60:63], v[150:153], v[166:169], v[60:63]
	v_mfma_f32_16x16x32_bf16 v[56:59], v[158:161], v[166:169], v[56:59]
	v_mfma_f32_16x16x32_bf16 v[52:55], v[150:153], v[182:185], v[52:55]
	v_mfma_f32_16x16x32_bf16 v[48:51], v[158:161], v[182:185], v[48:51]
	v_mfma_f32_16x16x32_bf16 v[44:47], v[150:153], v[190:193], v[44:47]
	v_mfma_f32_16x16x32_bf16 v[40:43], v[158:161], v[190:193], v[40:43]
	v_mfma_f32_16x16x32_bf16 v[36:39], v[150:153], v[198:201], v[36:39]
	v_mfma_f32_16x16x32_bf16 v[32:35], v[158:161], v[198:201], v[32:35]
	v_mfma_f32_16x16x32_bf16 v[60:63], v[154:157], v[178:181], v[60:63]
	v_mfma_f32_16x16x32_bf16 v[56:59], v[162:165], v[178:181], v[56:59]
	v_mfma_f32_16x16x32_bf16 v[52:55], v[154:157], v[186:189], v[52:55]
	v_mfma_f32_16x16x32_bf16 v[48:51], v[162:165], v[186:189], v[48:51]
	v_mfma_f32_16x16x32_bf16 v[44:47], v[154:157], v[194:197], v[44:47]
	v_mfma_f32_16x16x32_bf16 v[40:43], v[162:165], v[194:197], v[40:43]
	v_mfma_f32_16x16x32_bf16 v[36:39], v[154:157], v[202:205], v[36:39]
	v_mfma_f32_16x16x32_bf16 v[32:35], v[162:165], v[202:205], v[32:35]
	s_setprio 0
	s_barrier
	s_add_u32 s72, s36, 0x40000
	s_addc_u32 s73, s37, 0
	s_add_i32 s33, s66, s53
	v_lshl_add_u64 v[150:151], s[72:73], 0, v[130:131]
	s_mov_b32 m0, s33
	s_nop 0
	global_load_lds_dwordx4 v[150:151], off
	v_lshl_add_u64 v[150:151], s[72:73], 0, v[128:129]
	s_add_i32 m0, s33, 0x2000
	s_nop 0
	global_load_lds_dwordx4 v[150:151], off
	s_waitcnt vmcnt(6)
	s_barrier
	s_setprio 1
	v_mfma_f32_16x16x32_bf16 v[28:31], v[206:209], v[166:169], v[28:31]
	v_mfma_f32_16x16x32_bf16 v[24:27], v[214:217], v[166:169], v[24:27]
	v_mfma_f32_16x16x32_bf16 v[20:23], v[206:209], v[182:185], v[20:23]
	v_mfma_f32_16x16x32_bf16 v[16:19], v[214:217], v[182:185], v[16:19]
	v_mfma_f32_16x16x32_bf16 v[12:15], v[206:209], v[190:193], v[12:15]
	v_mfma_f32_16x16x32_bf16 v[8:11], v[214:217], v[190:193], v[8:11]
	v_mfma_f32_16x16x32_bf16 v[4:7], v[206:209], v[198:201], v[4:7]
	v_mfma_f32_16x16x32_bf16 v[0:3], v[214:217], v[198:201], v[0:3]
	v_mfma_f32_16x16x32_bf16 v[28:31], v[210:213], v[178:181], v[28:31]
	v_mfma_f32_16x16x32_bf16 v[24:27], v[218:221], v[178:181], v[24:27]
	v_mfma_f32_16x16x32_bf16 v[20:23], v[210:213], v[186:189], v[20:23]
	v_mfma_f32_16x16x32_bf16 v[16:19], v[218:221], v[186:189], v[16:19]
	v_mfma_f32_16x16x32_bf16 v[12:15], v[210:213], v[194:197], v[12:15]
	v_mfma_f32_16x16x32_bf16 v[8:11], v[218:221], v[194:197], v[8:11]
	v_mfma_f32_16x16x32_bf16 v[4:7], v[210:213], v[202:205], v[4:7]
	v_mfma_f32_16x16x32_bf16 v[0:3], v[218:221], v[202:205], v[0:3]
	s_setprio 0
	s_add_i32 s33, 0, 0x18000
	v_add_u32_e32 v132, s33, v143
	s_barrier
	ds_read_b128 v[150:153], v132
	ds_read_b128 v[154:157], v132 offset:1024
	ds_read_b128 v[158:161], v132 offset:2048
	ds_read_b128 v[162:165], v132 offset:3072
	s_add_u32 s40, s40, 0x40000
	s_addc_u32 s41, s41, 0
	s_mov_b32 m0, s56
	v_lshl_add_u64 v[206:207], s[40:41], 0, v[130:131]
	ds_read_b128 v[166:169], v146 offset:32768
	ds_read_b128 v[178:181], v146 offset:33792
	ds_read_b128 v[182:185], v146 offset:34816
	ds_read_b128 v[186:189], v146 offset:35840
	ds_read_b128 v[190:193], v146 offset:36864
	ds_read_b128 v[194:197], v146 offset:37888
	ds_read_b128 v[198:201], v146 offset:38912
	ds_read_b128 v[202:205], v146 offset:39936
	global_load_lds_dwordx4 v[206:207], off
	v_lshl_add_u64 v[206:207], s[40:41], 0, v[128:129]
	s_mov_b32 m0, s57
	s_nop 0
	global_load_lds_dwordx4 v[206:207], off
	s_waitcnt lgkmcnt(8)
	s_barrier
	s_waitcnt lgkmcnt(0)
	s_setprio 1
	s_waitcnt lgkmcnt(0)
	v_mfma_f32_16x16x32_bf16 v[124:127], v[150:153], v[166:169], v[124:127]
	v_mfma_f32_16x16x32_bf16 v[120:123], v[158:161], v[166:169], v[120:123]
	v_mfma_f32_16x16x32_bf16 v[116:119], v[150:153], v[182:185], v[116:119]
	v_mfma_f32_16x16x32_bf16 v[112:115], v[158:161], v[182:185], v[112:115]
	v_mfma_f32_16x16x32_bf16 v[108:111], v[150:153], v[190:193], v[108:111]
	v_mfma_f32_16x16x32_bf16 v[104:107], v[158:161], v[190:193], v[104:107]
	v_mfma_f32_16x16x32_bf16 v[100:103], v[150:153], v[198:201], v[100:103]
	v_mfma_f32_16x16x32_bf16 v[96:99], v[158:161], v[198:201], v[96:99]
	v_mfma_f32_16x16x32_bf16 v[124:127], v[154:157], v[178:181], v[124:127]
	v_mfma_f32_16x16x32_bf16 v[120:123], v[162:165], v[178:181], v[120:123]
	v_mfma_f32_16x16x32_bf16 v[116:119], v[154:157], v[186:189], v[116:119]
	v_mfma_f32_16x16x32_bf16 v[112:115], v[162:165], v[186:189], v[112:115]
	v_mfma_f32_16x16x32_bf16 v[108:111], v[154:157], v[194:197], v[108:111]
	v_mfma_f32_16x16x32_bf16 v[104:107], v[162:165], v[194:197], v[104:107]
	v_mfma_f32_16x16x32_bf16 v[100:103], v[154:157], v[202:205], v[100:103]
	v_mfma_f32_16x16x32_bf16 v[96:99], v[162:165], v[202:205], v[96:99]
	s_setprio 0
	s_barrier
	s_add_i32 s40, 0, 0x1c000
	s_add_i32 s33, s33, s53
	v_add_u32_e32 v132, s40, v143
	v_lshl_add_u64 v[222:223], v[222:223], 0, s[12:13]
	s_mov_b32 m0, s33
	ds_read_b128 v[206:209], v132
	ds_read_b128 v[210:213], v132 offset:1024
	ds_read_b128 v[214:217], v132 offset:2048
	ds_read_b128 v[218:221], v132 offset:3072
	global_load_lds_dwordx4 v[222:223], off
	v_lshl_add_u64 v[222:223], v[224:225], 0, s[12:13]
	s_add_i32 m0, s33, 0x2000
	s_nop 0
	global_load_lds_dwordx4 v[222:223], off
	s_barrier
	s_waitcnt lgkmcnt(0)
	s_setprio 1
	s_waitcnt lgkmcnt(0)
	v_mfma_f32_16x16x32_bf16 v[92:95], v[206:209], v[166:169], v[92:95]
	v_mfma_f32_16x16x32_bf16 v[88:91], v[214:217], v[166:169], v[88:91]
	v_mfma_f32_16x16x32_bf16 v[84:87], v[206:209], v[182:185], v[84:87]
	v_mfma_f32_16x16x32_bf16 v[80:83], v[214:217], v[182:185], v[80:83]
	v_mfma_f32_16x16x32_bf16 v[76:79], v[206:209], v[190:193], v[76:79]
	v_mfma_f32_16x16x32_bf16 v[72:75], v[214:217], v[190:193], v[72:75]
	v_mfma_f32_16x16x32_bf16 v[68:71], v[206:209], v[198:201], v[68:71]
	v_mfma_f32_16x16x32_bf16 v[64:67], v[214:217], v[198:201], v[64:67]
	v_mfma_f32_16x16x32_bf16 v[92:95], v[210:213], v[178:181], v[92:95]
	v_mfma_f32_16x16x32_bf16 v[88:91], v[218:221], v[178:181], v[88:91]
	v_mfma_f32_16x16x32_bf16 v[84:87], v[210:213], v[186:189], v[84:87]
	v_mfma_f32_16x16x32_bf16 v[80:83], v[218:221], v[186:189], v[80:83]
	v_mfma_f32_16x16x32_bf16 v[76:79], v[210:213], v[194:197], v[76:79]
	v_mfma_f32_16x16x32_bf16 v[72:75], v[218:221], v[194:197], v[72:75]
	v_mfma_f32_16x16x32_bf16 v[68:71], v[210:213], v[202:205], v[68:71]
	v_mfma_f32_16x16x32_bf16 v[64:67], v[218:221], v[202:205], v[64:67]
	s_setprio 0
	s_mov_b32 m0, s61
	v_lshl_add_u64 v[222:223], v[226:227], 0, s[12:13]
	s_barrier
	ds_read_b128 v[166:169], v146 offset:49152
	ds_read_b128 v[178:181], v146 offset:50176
	ds_read_b128 v[182:185], v146 offset:51200
	ds_read_b128 v[186:189], v146 offset:52224
	ds_read_b128 v[190:193], v146 offset:53248
	ds_read_b128 v[194:197], v146 offset:54272
	ds_read_b128 v[198:201], v146 offset:55296
	ds_read_b128 v[202:205], v146 offset:56320
	global_load_lds_dwordx4 v[222:223], off
	v_lshl_add_u64 v[222:223], v[228:229], 0, s[12:13]
	s_mov_b32 m0, s62
	s_nop 0
	global_load_lds_dwordx4 v[222:223], off
	s_barrier
	s_waitcnt lgkmcnt(0)
	s_setprio 1
	s_waitcnt lgkmcnt(0)
	v_mfma_f32_16x16x32_bf16 v[60:63], v[150:153], v[166:169], v[60:63]
	v_mfma_f32_16x16x32_bf16 v[56:59], v[158:161], v[166:169], v[56:59]
	v_mfma_f32_16x16x32_bf16 v[52:55], v[150:153], v[182:185], v[52:55]
	v_mfma_f32_16x16x32_bf16 v[48:51], v[158:161], v[182:185], v[48:51]
	v_mfma_f32_16x16x32_bf16 v[44:47], v[150:153], v[190:193], v[44:47]
	v_mfma_f32_16x16x32_bf16 v[40:43], v[158:161], v[190:193], v[40:43]
	v_mfma_f32_16x16x32_bf16 v[36:39], v[150:153], v[198:201], v[36:39]
	v_mfma_f32_16x16x32_bf16 v[32:35], v[158:161], v[198:201], v[32:35]
	v_mfma_f32_16x16x32_bf16 v[60:63], v[154:157], v[178:181], v[60:63]
	v_mfma_f32_16x16x32_bf16 v[56:59], v[162:165], v[178:181], v[56:59]
	v_mfma_f32_16x16x32_bf16 v[52:55], v[154:157], v[186:189], v[52:55]
	v_mfma_f32_16x16x32_bf16 v[48:51], v[162:165], v[186:189], v[48:51]
	v_mfma_f32_16x16x32_bf16 v[44:47], v[154:157], v[194:197], v[44:47]
	v_mfma_f32_16x16x32_bf16 v[40:43], v[162:165], v[194:197], v[40:43]
	v_mfma_f32_16x16x32_bf16 v[36:39], v[154:157], v[202:205], v[36:39]
	v_mfma_f32_16x16x32_bf16 v[32:35], v[162:165], v[202:205], v[32:35]
	s_setprio 0
	s_barrier
	s_add_u32 s36, s36, 0x40080
	s_addc_u32 s37, s37, 0
	s_add_i32 s33, s40, s53
	v_lshl_add_u64 v[150:151], s[36:37], 0, v[130:131]
	s_mov_b32 m0, s33
	s_nop 0
	global_load_lds_dwordx4 v[150:151], off
	v_lshl_add_u64 v[150:151], s[36:37], 0, v[128:129]
	s_add_i32 m0, s33, 0x2000
	s_nop 0
	global_load_lds_dwordx4 v[150:151], off
	s_waitcnt vmcnt(6)
	s_barrier
	s_setprio 1
	v_mfma_f32_16x16x32_bf16 v[28:31], v[206:209], v[166:169], v[28:31]
	v_mfma_f32_16x16x32_bf16 v[24:27], v[214:217], v[166:169], v[24:27]
	v_mfma_f32_16x16x32_bf16 v[20:23], v[206:209], v[182:185], v[20:23]
	v_mfma_f32_16x16x32_bf16 v[16:19], v[214:217], v[182:185], v[16:19]
	v_mfma_f32_16x16x32_bf16 v[12:15], v[206:209], v[190:193], v[12:15]
	v_mfma_f32_16x16x32_bf16 v[8:11], v[214:217], v[190:193], v[8:11]
	v_mfma_f32_16x16x32_bf16 v[4:7], v[206:209], v[198:201], v[4:7]
	v_mfma_f32_16x16x32_bf16 v[0:3], v[214:217], v[198:201], v[0:3]
	v_mfma_f32_16x16x32_bf16 v[28:31], v[210:213], v[178:181], v[28:31]
	v_mfma_f32_16x16x32_bf16 v[24:27], v[218:221], v[178:181], v[24:27]
	v_mfma_f32_16x16x32_bf16 v[20:23], v[210:213], v[186:189], v[20:23]
	v_mfma_f32_16x16x32_bf16 v[16:19], v[218:221], v[186:189], v[16:19]
	v_mfma_f32_16x16x32_bf16 v[12:15], v[210:213], v[194:197], v[12:15]
	v_mfma_f32_16x16x32_bf16 v[8:11], v[218:221], v[194:197], v[8:11]
	v_mfma_f32_16x16x32_bf16 v[4:7], v[210:213], v[202:205], v[4:7]
	v_mfma_f32_16x16x32_bf16 v[0:3], v[218:221], v[202:205], v[0:3]
	s_setprio 0
	s_add_i32 s71, s71, 2
	s_add_u32 s69, s69, 0x100
	s_addc_u32 s70, s70, 0
	s_add_u32 s34, s34, 0x100
	s_addc_u32 s35, s35, 0
	s_cmp_gt_u32 s71, 13
	s_barrier
	s_cbranch_scc0 .LBB0_1396
	s_lshl_b32 s23, s30, 21
	s_lshl_b32 s25, s31, 17
	s_add_i32 s23, s23, s25
	s_lshl_b32 s25, s59, 7
	s_add_i32 s23, s23, s25
	s_lshr_b32 s25, s60, 6
	s_lshl_b32 s25, s25, 15
	s_add_i32 s23, s23, s25
	s_bfe_u32 s25, s60, 0x10005
	s_lshl_b32 s25, s25, 6
	s_add_i32 s23, s23, s25
	v_lshl_add_u32 v132, v142, 7, s23
	v_lshl_add_u32 v132, v144, 2, v132
	v_lshrrev_b32_e32 v152, 2, v144
	v_and_b32_e32 v149, 1, v152
	v_lshrrev_b32_e32 v150, 1, v152
	v_lshl_or_b32 v149, v149, 1, v150
	v_xor_b32_e32 v150, 2, v149
	v_lshl_add_u32 v149, v149, 4, v142
	v_lshl_add_u32 v150, v150, 4, v142
	v_lshlrev_b32_e32 v149, 2, v149
	v_lshlrev_b32_e32 v150, 2, v150
	v_and_b32_e32 v151, 4, v144
	v_cmp_ne_u32_e64 s[34:35], 0, v151
	v_cmp_lt_u32_e64 s[36:37], 4, v144
	v_max_f32_e32 v124, v124, v124
	v_max_f32_e32 v125, v125, v125
	v_max_f32_e32 v126, v126, v126
	v_max_f32_e32 v127, v127, v127
	v_max_f32_e32 v124, 0, v124
	v_max_f32_e32 v125, 0, v125
	v_max_f32_e32 v126, 0, v126
	v_max_f32_e32 v127, 0, v127
	v_pk_mul_f32 v[124:125], v[124:125], v[124:125]
	v_pk_mul_f32 v[126:127], v[126:127], v[126:127]
	v_cvt_pk_bf16_f32 v124, v124, v125
	v_cvt_pk_bf16_f32 v125, v126, v127
	v_max_f32_e32 v120, v120, v120
	v_max_f32_e32 v121, v121, v121
	v_max_f32_e32 v122, v122, v122
	v_max_f32_e32 v123, v123, v123
	v_max_f32_e32 v120, 0, v120
	v_max_f32_e32 v121, 0, v121
	v_max_f32_e32 v122, 0, v122
	v_max_f32_e32 v123, 0, v123
	v_pk_mul_f32 v[120:121], v[120:121], v[120:121]
	v_pk_mul_f32 v[122:123], v[122:123], v[122:123]
	v_cvt_pk_bf16_f32 v120, v120, v121
	v_cvt_pk_bf16_f32 v121, v122, v123
	v_cndmask_b32_e64 v126, v124, v120, s[34:35]
	v_cndmask_b32_e64 v127, v125, v121, s[34:35]
	v_cndmask_b32_e64 v122, v120, v124, s[34:35]
	v_cndmask_b32_e64 v123, v121, v125, s[34:35]
	ds_permute_b32 v124, v149, v126
	ds_permute_b32 v125, v149, v127
	ds_permute_b32 v120, v150, v122
	ds_permute_b32 v121, v150, v123
	v_max_f32_e32 v92, v92, v92
	v_max_f32_e32 v93, v93, v93
	v_max_f32_e32 v94, v94, v94
	v_max_f32_e32 v95, v95, v95
	v_max_f32_e32 v92, 0, v92
	v_max_f32_e32 v93, 0, v93
	v_max_f32_e32 v94, 0, v94
	v_max_f32_e32 v95, 0, v95
	v_pk_mul_f32 v[92:93], v[92:93], v[92:93]
	v_pk_mul_f32 v[94:95], v[94:95], v[94:95]
	v_cvt_pk_bf16_f32 v92, v92, v93
	v_cvt_pk_bf16_f32 v93, v94, v95
	v_max_f32_e32 v88, v88, v88
	v_max_f32_e32 v89, v89, v89
	v_max_f32_e32 v90, v90, v90
	v_max_f32_e32 v91, v91, v91
	v_max_f32_e32 v88, 0, v88
	v_max_f32_e32 v89, 0, v89
	v_max_f32_e32 v90, 0, v90
	v_max_f32_e32 v91, 0, v91
	v_pk_mul_f32 v[88:89], v[88:89], v[88:89]
	v_pk_mul_f32 v[90:91], v[90:91], v[90:91]
	v_cvt_pk_bf16_f32 v88, v88, v89
	v_cvt_pk_bf16_f32 v89, v90, v91
	v_cndmask_b32_e64 v94, v92, v88, s[34:35]
	v_cndmask_b32_e64 v95, v93, v89, s[34:35]
	v_cndmask_b32_e64 v90, v88, v92, s[34:35]
	v_cndmask_b32_e64 v91, v89, v93, s[34:35]
	ds_permute_b32 v92, v149, v94
	ds_permute_b32 v93, v149, v95
	ds_permute_b32 v88, v150, v90
	ds_permute_b32 v89, v150, v91
	s_waitcnt lgkmcnt(4)
	v_cndmask_b32_e64 v126, v120, v124, s[36:37]
	v_cndmask_b32_e64 v127, v121, v125, s[36:37]
	v_cndmask_b32_e64 v124, v124, v120, s[36:37]
	v_cndmask_b32_e64 v125, v125, v121, s[36:37]
	global_store_dwordx4 v132, v[124:127], s[16:17]
	v_max_f32_e32 v116, v116, v116
	v_max_f32_e32 v117, v117, v117
	v_max_f32_e32 v118, v118, v118
	v_max_f32_e32 v119, v119, v119
	v_max_f32_e32 v116, 0, v116
	v_max_f32_e32 v117, 0, v117
	v_max_f32_e32 v118, 0, v118
	v_max_f32_e32 v119, 0, v119
	v_pk_mul_f32 v[116:117], v[116:117], v[116:117]
	v_pk_mul_f32 v[118:119], v[118:119], v[118:119]
	v_cvt_pk_bf16_f32 v116, v116, v117
	v_cvt_pk_bf16_f32 v117, v118, v119
	v_max_f32_e32 v112, v112, v112
	v_max_f32_e32 v113, v113, v113
	v_max_f32_e32 v114, v114, v114
	v_max_f32_e32 v115, v115, v115
	v_max_f32_e32 v112, 0, v112
	v_max_f32_e32 v113, 0, v113
	v_max_f32_e32 v114, 0, v114
	v_max_f32_e32 v115, 0, v115
	v_pk_mul_f32 v[112:113], v[112:113], v[112:113]
	v_pk_mul_f32 v[114:115], v[114:115], v[114:115]
	v_cvt_pk_bf16_f32 v112, v112, v113
	v_cvt_pk_bf16_f32 v113, v114, v115
	v_cndmask_b32_e64 v118, v116, v112, s[34:35]
	v_cndmask_b32_e64 v119, v117, v113, s[34:35]
	v_cndmask_b32_e64 v114, v112, v116, s[34:35]
	v_cndmask_b32_e64 v115, v113, v117, s[34:35]
	ds_permute_b32 v116, v149, v118
	ds_permute_b32 v117, v149, v119
	ds_permute_b32 v112, v150, v114
	ds_permute_b32 v113, v150, v115
	s_waitcnt lgkmcnt(4)
	v_cndmask_b32_e64 v94, v88, v92, s[36:37]
	v_cndmask_b32_e64 v95, v89, v93, s[36:37]
	v_cndmask_b32_e64 v92, v92, v88, s[36:37]
	v_cndmask_b32_e64 v93, v93, v89, s[36:37]
	v_add_u32_e32 v151, 0x10000, v132
	global_store_dwordx4 v151, v[92:95], s[16:17]
	v_max_f32_e32 v84, v84, v84
	v_max_f32_e32 v85, v85, v85
	v_max_f32_e32 v86, v86, v86
	v_max_f32_e32 v87, v87, v87
	v_max_f32_e32 v84, 0, v84
	v_max_f32_e32 v85, 0, v85
	v_max_f32_e32 v86, 0, v86
	v_max_f32_e32 v87, 0, v87
	v_pk_mul_f32 v[84:85], v[84:85], v[84:85]
	v_pk_mul_f32 v[86:87], v[86:87], v[86:87]
	v_cvt_pk_bf16_f32 v84, v84, v85
	v_cvt_pk_bf16_f32 v85, v86, v87
	v_max_f32_e32 v80, v80, v80
	v_max_f32_e32 v81, v81, v81
	v_max_f32_e32 v82, v82, v82
	v_max_f32_e32 v83, v83, v83
	v_max_f32_e32 v80, 0, v80
	v_max_f32_e32 v81, 0, v81
	v_max_f32_e32 v82, 0, v82
	v_max_f32_e32 v83, 0, v83
	v_pk_mul_f32 v[80:81], v[80:81], v[80:81]
	v_pk_mul_f32 v[82:83], v[82:83], v[82:83]
	v_cvt_pk_bf16_f32 v80, v80, v81
	v_cvt_pk_bf16_f32 v81, v82, v83
	v_cndmask_b32_e64 v86, v84, v80, s[34:35]
	v_cndmask_b32_e64 v87, v85, v81, s[34:35]
	v_cndmask_b32_e64 v82, v80, v84, s[34:35]
	v_cndmask_b32_e64 v83, v81, v85, s[34:35]
	ds_permute_b32 v84, v149, v86
	ds_permute_b32 v85, v149, v87
	ds_permute_b32 v80, v150, v82
	ds_permute_b32 v81, v150, v83
	s_waitcnt lgkmcnt(4)
	v_cndmask_b32_e64 v118, v112, v116, s[36:37]
	v_cndmask_b32_e64 v119, v113, v117, s[36:37]
	v_cndmask_b32_e64 v116, v116, v112, s[36:37]
	v_cndmask_b32_e64 v117, v117, v113, s[36:37]
	v_add_u32_e32 v151, 0x800, v132
	global_store_dwordx4 v151, v[116:119], s[16:17]
	v_max_f32_e32 v108, v108, v108
	v_max_f32_e32 v109, v109, v109
	v_max_f32_e32 v110, v110, v110
	v_max_f32_e32 v111, v111, v111
	v_max_f32_e32 v108, 0, v108
	v_max_f32_e32 v109, 0, v109
	v_max_f32_e32 v110, 0, v110
	v_max_f32_e32 v111, 0, v111
	v_pk_mul_f32 v[108:109], v[108:109], v[108:109]
	v_pk_mul_f32 v[110:111], v[110:111], v[110:111]
	v_cvt_pk_bf16_f32 v108, v108, v109
	v_cvt_pk_bf16_f32 v109, v110, v111
	v_max_f32_e32 v104, v104, v104
	v_max_f32_e32 v105, v105, v105
	v_max_f32_e32 v106, v106, v106
	v_max_f32_e32 v107, v107, v107
	v_max_f32_e32 v104, 0, v104
	v_max_f32_e32 v105, 0, v105
	v_max_f32_e32 v106, 0, v106
	v_max_f32_e32 v107, 0, v107
	v_pk_mul_f32 v[104:105], v[104:105], v[104:105]
	v_pk_mul_f32 v[106:107], v[106:107], v[106:107]
	v_cvt_pk_bf16_f32 v104, v104, v105
	v_cvt_pk_bf16_f32 v105, v106, v107
	v_cndmask_b32_e64 v110, v108, v104, s[34:35]
	v_cndmask_b32_e64 v111, v109, v105, s[34:35]
	v_cndmask_b32_e64 v106, v104, v108, s[34:35]
	v_cndmask_b32_e64 v107, v105, v109, s[34:35]
	ds_permute_b32 v108, v149, v110
	ds_permute_b32 v109, v149, v111
	ds_permute_b32 v104, v150, v106
	ds_permute_b32 v105, v150, v107
	s_waitcnt lgkmcnt(4)
	v_cndmask_b32_e64 v86, v80, v84, s[36:37]
	v_cndmask_b32_e64 v87, v81, v85, s[36:37]
	v_cndmask_b32_e64 v84, v84, v80, s[36:37]
	v_cndmask_b32_e64 v85, v85, v81, s[36:37]
	v_add_u32_e32 v151, 0x10800, v132
	global_store_dwordx4 v151, v[84:87], s[16:17]
	v_max_f32_e32 v76, v76, v76
	v_max_f32_e32 v77, v77, v77
	v_max_f32_e32 v78, v78, v78
	v_max_f32_e32 v79, v79, v79
	v_max_f32_e32 v76, 0, v76
	v_max_f32_e32 v77, 0, v77
	v_max_f32_e32 v78, 0, v78
	v_max_f32_e32 v79, 0, v79
	v_pk_mul_f32 v[76:77], v[76:77], v[76:77]
	v_pk_mul_f32 v[78:79], v[78:79], v[78:79]
	v_cvt_pk_bf16_f32 v76, v76, v77
	v_cvt_pk_bf16_f32 v77, v78, v79
	v_max_f32_e32 v72, v72, v72
	v_max_f32_e32 v73, v73, v73
	v_max_f32_e32 v74, v74, v74
	v_max_f32_e32 v75, v75, v75
	v_max_f32_e32 v72, 0, v72
	v_max_f32_e32 v73, 0, v73
	v_max_f32_e32 v74, 0, v74
	v_max_f32_e32 v75, 0, v75
	v_pk_mul_f32 v[72:73], v[72:73], v[72:73]
	v_pk_mul_f32 v[74:75], v[74:75], v[74:75]
	v_cvt_pk_bf16_f32 v72, v72, v73
	v_cvt_pk_bf16_f32 v73, v74, v75
	v_cndmask_b32_e64 v78, v76, v72, s[34:35]
	v_cndmask_b32_e64 v79, v77, v73, s[34:35]
	v_cndmask_b32_e64 v74, v72, v76, s[34:35]
	v_cndmask_b32_e64 v75, v73, v77, s[34:35]
	ds_permute_b32 v76, v149, v78
	ds_permute_b32 v77, v149, v79
	ds_permute_b32 v72, v150, v74
	ds_permute_b32 v73, v150, v75
	s_waitcnt lgkmcnt(4)
	v_cndmask_b32_e64 v110, v104, v108, s[36:37]
	v_cndmask_b32_e64 v111, v105, v109, s[36:37]
	v_cndmask_b32_e64 v108, v108, v104, s[36:37]
	v_cndmask_b32_e64 v109, v109, v105, s[36:37]
	v_add_u32_e32 v151, 0x1000, v132
	global_store_dwordx4 v151, v[108:111], s[16:17]
	v_max_f32_e32 v100, v100, v100
	v_max_f32_e32 v101, v101, v101
	v_max_f32_e32 v102, v102, v102
	v_max_f32_e32 v103, v103, v103
	v_max_f32_e32 v100, 0, v100
	v_max_f32_e32 v101, 0, v101
	v_max_f32_e32 v102, 0, v102
	v_max_f32_e32 v103, 0, v103
	v_pk_mul_f32 v[100:101], v[100:101], v[100:101]
	v_pk_mul_f32 v[102:103], v[102:103], v[102:103]
	v_cvt_pk_bf16_f32 v100, v100, v101
	v_cvt_pk_bf16_f32 v101, v102, v103
	v_max_f32_e32 v96, v96, v96
	v_max_f32_e32 v97, v97, v97
	v_max_f32_e32 v98, v98, v98
	v_max_f32_e32 v99, v99, v99
	v_max_f32_e32 v96, 0, v96
	v_max_f32_e32 v97, 0, v97
	v_max_f32_e32 v98, 0, v98
	v_max_f32_e32 v99, 0, v99
	v_pk_mul_f32 v[96:97], v[96:97], v[96:97]
	v_pk_mul_f32 v[98:99], v[98:99], v[98:99]
	v_cvt_pk_bf16_f32 v96, v96, v97
	v_cvt_pk_bf16_f32 v97, v98, v99
	v_cndmask_b32_e64 v102, v100, v96, s[34:35]
	v_cndmask_b32_e64 v103, v101, v97, s[34:35]
	v_cndmask_b32_e64 v98, v96, v100, s[34:35]
	v_cndmask_b32_e64 v99, v97, v101, s[34:35]
	ds_permute_b32 v100, v149, v102
	ds_permute_b32 v101, v149, v103
	ds_permute_b32 v96, v150, v98
	ds_permute_b32 v97, v150, v99
	s_waitcnt lgkmcnt(4)
	v_cndmask_b32_e64 v78, v72, v76, s[36:37]
	v_cndmask_b32_e64 v79, v73, v77, s[36:37]
	v_cndmask_b32_e64 v76, v76, v72, s[36:37]
	v_cndmask_b32_e64 v77, v77, v73, s[36:37]
	v_add_u32_e32 v151, 0x11000, v132
	global_store_dwordx4 v151, v[76:79], s[16:17]
	v_max_f32_e32 v68, v68, v68
	v_max_f32_e32 v69, v69, v69
	v_max_f32_e32 v70, v70, v70
	v_max_f32_e32 v71, v71, v71
	v_max_f32_e32 v68, 0, v68
	v_max_f32_e32 v69, 0, v69
	v_max_f32_e32 v70, 0, v70
	v_max_f32_e32 v71, 0, v71
	v_pk_mul_f32 v[68:69], v[68:69], v[68:69]
	v_pk_mul_f32 v[70:71], v[70:71], v[70:71]
	v_cvt_pk_bf16_f32 v68, v68, v69
	v_cvt_pk_bf16_f32 v69, v70, v71
	v_max_f32_e32 v64, v64, v64
	v_max_f32_e32 v65, v65, v65
	v_max_f32_e32 v66, v66, v66
	v_max_f32_e32 v67, v67, v67
	v_max_f32_e32 v64, 0, v64
	v_max_f32_e32 v65, 0, v65
	v_max_f32_e32 v66, 0, v66
	v_max_f32_e32 v67, 0, v67
	v_pk_mul_f32 v[64:65], v[64:65], v[64:65]
	v_pk_mul_f32 v[66:67], v[66:67], v[66:67]
	v_cvt_pk_bf16_f32 v64, v64, v65
	v_cvt_pk_bf16_f32 v65, v66, v67
	v_cndmask_b32_e64 v70, v68, v64, s[34:35]
	v_cndmask_b32_e64 v71, v69, v65, s[34:35]
	v_cndmask_b32_e64 v66, v64, v68, s[34:35]
	v_cndmask_b32_e64 v67, v65, v69, s[34:35]
	ds_permute_b32 v68, v149, v70
	ds_permute_b32 v69, v149, v71
	ds_permute_b32 v64, v150, v66
	ds_permute_b32 v65, v150, v67
	s_waitcnt lgkmcnt(4)
	v_cndmask_b32_e64 v102, v96, v100, s[36:37]
	v_cndmask_b32_e64 v103, v97, v101, s[36:37]
	v_cndmask_b32_e64 v100, v100, v96, s[36:37]
	v_cndmask_b32_e64 v101, v101, v97, s[36:37]
	v_add_u32_e32 v151, 0x1800, v132
	global_store_dwordx4 v151, v[100:103], s[16:17]
	v_max_f32_e32 v60, v60, v60
	v_max_f32_e32 v61, v61, v61
	v_max_f32_e32 v62, v62, v62
	v_max_f32_e32 v63, v63, v63
	v_max_f32_e32 v60, 0, v60
	v_max_f32_e32 v61, 0, v61
	v_max_f32_e32 v62, 0, v62
	v_max_f32_e32 v63, 0, v63
	v_pk_mul_f32 v[60:61], v[60:61], v[60:61]
	v_pk_mul_f32 v[62:63], v[62:63], v[62:63]
	v_cvt_pk_bf16_f32 v60, v60, v61
	v_cvt_pk_bf16_f32 v61, v62, v63
	v_max_f32_e32 v56, v56, v56
	v_max_f32_e32 v57, v57, v57
	v_max_f32_e32 v58, v58, v58
	v_max_f32_e32 v59, v59, v59
	v_max_f32_e32 v56, 0, v56
	v_max_f32_e32 v57, 0, v57
	v_max_f32_e32 v58, 0, v58
	v_max_f32_e32 v59, 0, v59
	v_pk_mul_f32 v[56:57], v[56:57], v[56:57]
	v_pk_mul_f32 v[58:59], v[58:59], v[58:59]
	v_cvt_pk_bf16_f32 v56, v56, v57
	v_cvt_pk_bf16_f32 v57, v58, v59
	v_cndmask_b32_e64 v62, v60, v56, s[34:35]
	v_cndmask_b32_e64 v63, v61, v57, s[34:35]
	v_cndmask_b32_e64 v58, v56, v60, s[34:35]
	v_cndmask_b32_e64 v59, v57, v61, s[34:35]
	ds_permute_b32 v60, v149, v62
	ds_permute_b32 v61, v149, v63
	ds_permute_b32 v56, v150, v58
	ds_permute_b32 v57, v150, v59
	s_waitcnt lgkmcnt(4)
	v_cndmask_b32_e64 v70, v64, v68, s[36:37]
	v_cndmask_b32_e64 v71, v65, v69, s[36:37]
	v_cndmask_b32_e64 v68, v68, v64, s[36:37]
	v_cndmask_b32_e64 v69, v69, v65, s[36:37]
	v_add_u32_e32 v151, 0x11800, v132
	global_store_dwordx4 v151, v[68:71], s[16:17]
	v_max_f32_e32 v28, v28, v28
	v_max_f32_e32 v29, v29, v29
	v_max_f32_e32 v30, v30, v30
	v_max_f32_e32 v31, v31, v31
	v_max_f32_e32 v28, 0, v28
	v_max_f32_e32 v29, 0, v29
	v_max_f32_e32 v30, 0, v30
	v_max_f32_e32 v31, 0, v31
	v_pk_mul_f32 v[28:29], v[28:29], v[28:29]
	v_pk_mul_f32 v[30:31], v[30:31], v[30:31]
	v_cvt_pk_bf16_f32 v28, v28, v29
	v_cvt_pk_bf16_f32 v29, v30, v31
	v_max_f32_e32 v24, v24, v24
	v_max_f32_e32 v25, v25, v25
	v_max_f32_e32 v26, v26, v26
	v_max_f32_e32 v27, v27, v27
	v_max_f32_e32 v24, 0, v24
	v_max_f32_e32 v25, 0, v25
	v_max_f32_e32 v26, 0, v26
	v_max_f32_e32 v27, 0, v27
	v_pk_mul_f32 v[24:25], v[24:25], v[24:25]
	v_pk_mul_f32 v[26:27], v[26:27], v[26:27]
	v_cvt_pk_bf16_f32 v24, v24, v25
	v_cvt_pk_bf16_f32 v25, v26, v27
	v_cndmask_b32_e64 v30, v28, v24, s[34:35]
	v_cndmask_b32_e64 v31, v29, v25, s[34:35]
	v_cndmask_b32_e64 v26, v24, v28, s[34:35]
	v_cndmask_b32_e64 v27, v25, v29, s[34:35]
	ds_permute_b32 v28, v149, v30
	ds_permute_b32 v29, v149, v31
	ds_permute_b32 v24, v150, v26
	ds_permute_b32 v25, v150, v27
	s_waitcnt lgkmcnt(4)
	v_cndmask_b32_e64 v62, v56, v60, s[36:37]
	v_cndmask_b32_e64 v63, v57, v61, s[36:37]
	v_cndmask_b32_e64 v60, v60, v56, s[36:37]
	v_cndmask_b32_e64 v61, v61, v57, s[36:37]
	v_add_u32_e32 v151, 0x4000, v132
	global_store_dwordx4 v151, v[60:63], s[16:17]
	v_max_f32_e32 v52, v52, v52
	v_max_f32_e32 v53, v53, v53
	v_max_f32_e32 v54, v54, v54
	v_max_f32_e32 v55, v55, v55
	v_max_f32_e32 v52, 0, v52
	v_max_f32_e32 v53, 0, v53
	v_max_f32_e32 v54, 0, v54
	v_max_f32_e32 v55, 0, v55
	v_pk_mul_f32 v[52:53], v[52:53], v[52:53]
	v_pk_mul_f32 v[54:55], v[54:55], v[54:55]
	v_cvt_pk_bf16_f32 v52, v52, v53
	v_cvt_pk_bf16_f32 v53, v54, v55
	v_max_f32_e32 v48, v48, v48
	v_max_f32_e32 v49, v49, v49
	v_max_f32_e32 v50, v50, v50
	v_max_f32_e32 v51, v51, v51
	v_max_f32_e32 v48, 0, v48
	v_max_f32_e32 v49, 0, v49
	v_max_f32_e32 v50, 0, v50
	v_max_f32_e32 v51, 0, v51
	v_pk_mul_f32 v[48:49], v[48:49], v[48:49]
	v_pk_mul_f32 v[50:51], v[50:51], v[50:51]
	v_cvt_pk_bf16_f32 v48, v48, v49
	v_cvt_pk_bf16_f32 v49, v50, v51
	v_cndmask_b32_e64 v54, v52, v48, s[34:35]
	v_cndmask_b32_e64 v55, v53, v49, s[34:35]
	v_cndmask_b32_e64 v50, v48, v52, s[34:35]
	v_cndmask_b32_e64 v51, v49, v53, s[34:35]
	ds_permute_b32 v52, v149, v54
	ds_permute_b32 v53, v149, v55
	ds_permute_b32 v48, v150, v50
	ds_permute_b32 v49, v150, v51
	s_waitcnt lgkmcnt(4)
	v_cndmask_b32_e64 v30, v24, v28, s[36:37]
	v_cndmask_b32_e64 v31, v25, v29, s[36:37]
	v_cndmask_b32_e64 v28, v28, v24, s[36:37]
	v_cndmask_b32_e64 v29, v29, v25, s[36:37]
	v_add_u32_e32 v151, 0x14000, v132
	global_store_dwordx4 v151, v[28:31], s[16:17]
	v_max_f32_e32 v20, v20, v20
	v_max_f32_e32 v21, v21, v21
	v_max_f32_e32 v22, v22, v22
	v_max_f32_e32 v23, v23, v23
	v_max_f32_e32 v20, 0, v20
	v_max_f32_e32 v21, 0, v21
	v_max_f32_e32 v22, 0, v22
	v_max_f32_e32 v23, 0, v23
	v_pk_mul_f32 v[20:21], v[20:21], v[20:21]
	v_pk_mul_f32 v[22:23], v[22:23], v[22:23]
	v_cvt_pk_bf16_f32 v20, v20, v21
	v_cvt_pk_bf16_f32 v21, v22, v23
	v_max_f32_e32 v16, v16, v16
	v_max_f32_e32 v17, v17, v17
	v_max_f32_e32 v18, v18, v18
	v_max_f32_e32 v19, v19, v19
	v_max_f32_e32 v16, 0, v16
	v_max_f32_e32 v17, 0, v17
	v_max_f32_e32 v18, 0, v18
	v_max_f32_e32 v19, 0, v19
	v_pk_mul_f32 v[16:17], v[16:17], v[16:17]
	v_pk_mul_f32 v[18:19], v[18:19], v[18:19]
	v_cvt_pk_bf16_f32 v16, v16, v17
	v_cvt_pk_bf16_f32 v17, v18, v19
	v_cndmask_b32_e64 v22, v20, v16, s[34:35]
	v_cndmask_b32_e64 v23, v21, v17, s[34:35]
	v_cndmask_b32_e64 v18, v16, v20, s[34:35]
	v_cndmask_b32_e64 v19, v17, v21, s[34:35]
	ds_permute_b32 v20, v149, v22
	ds_permute_b32 v21, v149, v23
	ds_permute_b32 v16, v150, v18
	ds_permute_b32 v17, v150, v19
	s_waitcnt lgkmcnt(4)
	v_cndmask_b32_e64 v54, v48, v52, s[36:37]
	v_cndmask_b32_e64 v55, v49, v53, s[36:37]
	v_cndmask_b32_e64 v52, v52, v48, s[36:37]
	v_cndmask_b32_e64 v53, v53, v49, s[36:37]
	v_add_u32_e32 v151, 0x4800, v132
	global_store_dwordx4 v151, v[52:55], s[16:17]
	v_max_f32_e32 v44, v44, v44
	v_max_f32_e32 v45, v45, v45
	v_max_f32_e32 v46, v46, v46
	v_max_f32_e32 v47, v47, v47
	v_max_f32_e32 v44, 0, v44
	v_max_f32_e32 v45, 0, v45
	v_max_f32_e32 v46, 0, v46
	v_max_f32_e32 v47, 0, v47
	v_pk_mul_f32 v[44:45], v[44:45], v[44:45]
	v_pk_mul_f32 v[46:47], v[46:47], v[46:47]
	v_cvt_pk_bf16_f32 v44, v44, v45
	v_cvt_pk_bf16_f32 v45, v46, v47
	v_max_f32_e32 v40, v40, v40
	v_max_f32_e32 v41, v41, v41
	v_max_f32_e32 v42, v42, v42
	v_max_f32_e32 v43, v43, v43
	v_max_f32_e32 v40, 0, v40
	v_max_f32_e32 v41, 0, v41
	v_max_f32_e32 v42, 0, v42
	v_max_f32_e32 v43, 0, v43
	v_pk_mul_f32 v[40:41], v[40:41], v[40:41]
	v_pk_mul_f32 v[42:43], v[42:43], v[42:43]
	v_cvt_pk_bf16_f32 v40, v40, v41
	v_cvt_pk_bf16_f32 v41, v42, v43
	v_cndmask_b32_e64 v46, v44, v40, s[34:35]
	v_cndmask_b32_e64 v47, v45, v41, s[34:35]
	v_cndmask_b32_e64 v42, v40, v44, s[34:35]
	v_cndmask_b32_e64 v43, v41, v45, s[34:35]
	ds_permute_b32 v44, v149, v46
	ds_permute_b32 v45, v149, v47
	ds_permute_b32 v40, v150, v42
	ds_permute_b32 v41, v150, v43
	s_waitcnt lgkmcnt(4)
	v_cndmask_b32_e64 v22, v16, v20, s[36:37]
	v_cndmask_b32_e64 v23, v17, v21, s[36:37]
	v_cndmask_b32_e64 v20, v20, v16, s[36:37]
	v_cndmask_b32_e64 v21, v21, v17, s[36:37]
	v_add_u32_e32 v151, 0x14800, v132
	global_store_dwordx4 v151, v[20:23], s[16:17]
	v_max_f32_e32 v12, v12, v12
	v_max_f32_e32 v13, v13, v13
	v_max_f32_e32 v14, v14, v14
	v_max_f32_e32 v15, v15, v15
	v_max_f32_e32 v12, 0, v12
	v_max_f32_e32 v13, 0, v13
	v_max_f32_e32 v14, 0, v14
	v_max_f32_e32 v15, 0, v15
	v_pk_mul_f32 v[12:13], v[12:13], v[12:13]
	v_pk_mul_f32 v[14:15], v[14:15], v[14:15]
	v_cvt_pk_bf16_f32 v12, v12, v13
	v_cvt_pk_bf16_f32 v13, v14, v15
	v_max_f32_e32 v8, v8, v8
	v_max_f32_e32 v9, v9, v9
	v_max_f32_e32 v10, v10, v10
	v_max_f32_e32 v11, v11, v11
	v_max_f32_e32 v8, 0, v8
	v_max_f32_e32 v9, 0, v9
	v_max_f32_e32 v10, 0, v10
	v_max_f32_e32 v11, 0, v11
	v_pk_mul_f32 v[8:9], v[8:9], v[8:9]
	v_pk_mul_f32 v[10:11], v[10:11], v[10:11]
	v_cvt_pk_bf16_f32 v8, v8, v9
	v_cvt_pk_bf16_f32 v9, v10, v11
	v_cndmask_b32_e64 v14, v12, v8, s[34:35]
	v_cndmask_b32_e64 v15, v13, v9, s[34:35]
	v_cndmask_b32_e64 v10, v8, v12, s[34:35]
	v_cndmask_b32_e64 v11, v9, v13, s[34:35]
	ds_permute_b32 v12, v149, v14
	ds_permute_b32 v13, v149, v15
	ds_permute_b32 v8, v150, v10
	ds_permute_b32 v9, v150, v11
	s_waitcnt lgkmcnt(4)
	v_cndmask_b32_e64 v46, v40, v44, s[36:37]
	v_cndmask_b32_e64 v47, v41, v45, s[36:37]
	v_cndmask_b32_e64 v44, v44, v40, s[36:37]
	v_cndmask_b32_e64 v45, v45, v41, s[36:37]
	v_add_u32_e32 v151, 0x5000, v132
	global_store_dwordx4 v151, v[44:47], s[16:17]
	v_max_f32_e32 v36, v36, v36
	v_max_f32_e32 v37, v37, v37
	v_max_f32_e32 v38, v38, v38
	v_max_f32_e32 v39, v39, v39
	v_max_f32_e32 v36, 0, v36
	v_max_f32_e32 v37, 0, v37
	v_max_f32_e32 v38, 0, v38
	v_max_f32_e32 v39, 0, v39
	v_pk_mul_f32 v[36:37], v[36:37], v[36:37]
	v_pk_mul_f32 v[38:39], v[38:39], v[38:39]
	v_cvt_pk_bf16_f32 v36, v36, v37
	v_cvt_pk_bf16_f32 v37, v38, v39
	v_max_f32_e32 v32, v32, v32
	v_max_f32_e32 v33, v33, v33
	v_max_f32_e32 v34, v34, v34
	v_max_f32_e32 v35, v35, v35
	v_max_f32_e32 v32, 0, v32
	v_max_f32_e32 v33, 0, v33
	v_max_f32_e32 v34, 0, v34
	v_max_f32_e32 v35, 0, v35
	v_pk_mul_f32 v[32:33], v[32:33], v[32:33]
	v_pk_mul_f32 v[34:35], v[34:35], v[34:35]
	v_cvt_pk_bf16_f32 v32, v32, v33
	v_cvt_pk_bf16_f32 v33, v34, v35
	v_cndmask_b32_e64 v38, v36, v32, s[34:35]
	v_cndmask_b32_e64 v39, v37, v33, s[34:35]
	v_cndmask_b32_e64 v34, v32, v36, s[34:35]
	v_cndmask_b32_e64 v35, v33, v37, s[34:35]
	ds_permute_b32 v36, v149, v38
	ds_permute_b32 v37, v149, v39
	ds_permute_b32 v32, v150, v34
	ds_permute_b32 v33, v150, v35
	s_waitcnt lgkmcnt(4)
	v_cndmask_b32_e64 v14, v8, v12, s[36:37]
	v_cndmask_b32_e64 v15, v9, v13, s[36:37]
	v_cndmask_b32_e64 v12, v12, v8, s[36:37]
	v_cndmask_b32_e64 v13, v13, v9, s[36:37]
	v_add_u32_e32 v151, 0x15000, v132
	global_store_dwordx4 v151, v[12:15], s[16:17]
	v_max_f32_e32 v4, v4, v4
	v_max_f32_e32 v5, v5, v5
	v_max_f32_e32 v6, v6, v6
	v_max_f32_e32 v7, v7, v7
	v_max_f32_e32 v4, 0, v4
	v_max_f32_e32 v5, 0, v5
	v_max_f32_e32 v6, 0, v6
	v_max_f32_e32 v7, 0, v7
	v_pk_mul_f32 v[4:5], v[4:5], v[4:5]
	v_pk_mul_f32 v[6:7], v[6:7], v[6:7]
	v_cvt_pk_bf16_f32 v4, v4, v5
	v_cvt_pk_bf16_f32 v5, v6, v7
	v_max_f32_e32 v0, v0, v0
	v_max_f32_e32 v1, v1, v1
	v_max_f32_e32 v2, v2, v2
	v_max_f32_e32 v3, v3, v3
	v_max_f32_e32 v0, 0, v0
	v_max_f32_e32 v1, 0, v1
	v_max_f32_e32 v2, 0, v2
	v_max_f32_e32 v3, 0, v3
	v_pk_mul_f32 v[0:1], v[0:1], v[0:1]
	v_pk_mul_f32 v[2:3], v[2:3], v[2:3]
	v_cvt_pk_bf16_f32 v0, v0, v1
	v_cvt_pk_bf16_f32 v1, v2, v3
	v_cndmask_b32_e64 v6, v4, v0, s[34:35]
	v_cndmask_b32_e64 v7, v5, v1, s[34:35]
	v_cndmask_b32_e64 v2, v0, v4, s[34:35]
	v_cndmask_b32_e64 v3, v1, v5, s[34:35]
	ds_permute_b32 v4, v149, v6
	ds_permute_b32 v5, v149, v7
	ds_permute_b32 v0, v150, v2
	ds_permute_b32 v1, v150, v3
	s_waitcnt lgkmcnt(4)
	v_cndmask_b32_e64 v38, v32, v36, s[36:37]
	v_cndmask_b32_e64 v39, v33, v37, s[36:37]
	v_cndmask_b32_e64 v36, v36, v32, s[36:37]
	v_cndmask_b32_e64 v37, v37, v33, s[36:37]
	v_add_u32_e32 v151, 0x5800, v132
	global_store_dwordx4 v151, v[36:39], s[16:17]
	s_waitcnt lgkmcnt(0)
	v_cndmask_b32_e64 v6, v0, v4, s[36:37]
	v_cndmask_b32_e64 v7, v1, v5, s[36:37]
	v_cndmask_b32_e64 v4, v4, v0, s[36:37]
	v_cndmask_b32_e64 v5, v5, v1, s[36:37]
	v_add_u32_e32 v151, 0x15800, v132
	global_store_dwordx4 v151, v[4:7], s[16:17]
	s_and_b64 vcc, exec, s[10:11]
	s_mov_b32 s31, s22
	s_mov_b32 s30, s24
	s_mov_b64 s[34:35], s[28:29]
	s_mov_b64 s[36:37], s[26:27]
	s_cbranch_vccz .LBB0_1393
	s_waitcnt vmcnt(0)
	s_cmpk_gt_u32 s45, 0xff
	s_cbranch_scc1 .LBB0_1400
	s_barrier

.LBB0_1985:
	ds_read_b128 v[150:153], v145
	ds_read_b128 v[154:157], v145 offset:1024
	ds_read_b128 v[158:161], v145 offset:2048
	ds_read_b128 v[162:165], v145 offset:3072
	s_add_u32 s33, s30, 0xfffc0080
	s_addc_u32 s34, s31, -1
	s_cmp_eq_u32 s69, 12
	s_cselect_b32 s37, s23, s34
	s_cselect_b32 s36, s65, s33
	s_cselect_b32 s35, s21, s68
	s_cselect_b32 s34, s66, s67
	v_lshl_add_u64 v[206:207], s[30:31], 0, v[136:137]
	s_add_i32 m0, s52, 0xc000
	ds_read_b128 v[166:169], v146
	ds_read_b128 v[178:181], v146 offset:1024
	ds_read_b128 v[182:185], v146 offset:2048
	ds_read_b128 v[186:189], v146 offset:3072
	ds_read_b128 v[190:193], v146 offset:4096
	ds_read_b128 v[194:197], v146 offset:5120
	ds_read_b128 v[198:201], v146 offset:6144
	ds_read_b128 v[202:205], v146 offset:7168
	global_load_lds_dwordx4 v[206:207], off
	v_lshl_add_u64 v[206:207], s[30:31], 0, v[134:135]
	s_add_i32 m0, s52, 0xe000
	s_nop 0
	global_load_lds_dwordx4 v[206:207], off
	s_waitcnt lgkmcnt(8)
	s_barrier
	s_waitcnt lgkmcnt(0)
	s_setprio 1
	s_waitcnt lgkmcnt(0)
	v_mfma_f32_16x16x32_bf16 v[124:127], v[150:153], v[166:169], v[124:127]
	v_mfma_f32_16x16x32_bf16 v[120:123], v[158:161], v[166:169], v[120:123]
	v_mfma_f32_16x16x32_bf16 v[116:119], v[150:153], v[182:185], v[116:119]
	v_mfma_f32_16x16x32_bf16 v[112:115], v[158:161], v[182:185], v[112:115]
	v_mfma_f32_16x16x32_bf16 v[108:111], v[150:153], v[190:193], v[108:111]
	v_mfma_f32_16x16x32_bf16 v[104:107], v[158:161], v[190:193], v[104:107]
	v_mfma_f32_16x16x32_bf16 v[100:103], v[150:153], v[198:201], v[100:103]
	v_mfma_f32_16x16x32_bf16 v[96:99], v[158:161], v[198:201], v[96:99]
	v_mfma_f32_16x16x32_bf16 v[124:127], v[154:157], v[178:181], v[124:127]
	v_mfma_f32_16x16x32_bf16 v[120:123], v[162:165], v[178:181], v[120:123]
	v_mfma_f32_16x16x32_bf16 v[116:119], v[154:157], v[186:189], v[116:119]
	v_mfma_f32_16x16x32_bf16 v[112:115], v[162:165], v[186:189], v[112:115]
	v_mfma_f32_16x16x32_bf16 v[108:111], v[154:157], v[194:197], v[108:111]
	v_mfma_f32_16x16x32_bf16 v[104:107], v[162:165], v[194:197], v[104:107]
	v_mfma_f32_16x16x32_bf16 v[100:103], v[154:157], v[202:205], v[100:103]
	v_mfma_f32_16x16x32_bf16 v[96:99], v[162:165], v[202:205], v[96:99]
	s_setprio 0
	s_barrier
	s_add_i32 s33, s63, s51
	v_lshl_add_u64 v[222:223], s[34:35], 0, v[130:131]
	s_mov_b32 m0, s33
	ds_read_b128 v[206:209], v147
	ds_read_b128 v[210:213], v147 offset:1024
	ds_read_b128 v[214:217], v147 offset:2048
	ds_read_b128 v[218:221], v147 offset:3072
	global_load_lds_dwordx4 v[222:223], off
	v_lshl_add_u64 v[224:225], s[34:35], 0, v[128:129]
	s_add_i32 m0, s33, 0x2000
	s_nop 0
	global_load_lds_dwordx4 v[224:225], off
	s_barrier
	s_waitcnt lgkmcnt(0)
	s_setprio 1
	s_waitcnt lgkmcnt(0)
	v_mfma_f32_16x16x32_bf16 v[92:95], v[206:209], v[166:169], v[92:95]
	v_mfma_f32_16x16x32_bf16 v[88:91], v[214:217], v[166:169], v[88:91]
	v_mfma_f32_16x16x32_bf16 v[84:87], v[206:209], v[182:185], v[84:87]
	v_mfma_f32_16x16x32_bf16 v[80:83], v[214:217], v[182:185], v[80:83]
	v_mfma_f32_16x16x32_bf16 v[76:79], v[206:209], v[190:193], v[76:79]
	v_mfma_f32_16x16x32_bf16 v[72:75], v[214:217], v[190:193], v[72:75]
	v_mfma_f32_16x16x32_bf16 v[68:71], v[206:209], v[198:201], v[68:71]
	v_mfma_f32_16x16x32_bf16 v[64:67], v[214:217], v[198:201], v[64:67]
	v_mfma_f32_16x16x32_bf16 v[92:95], v[210:213], v[178:181], v[92:95]
	v_mfma_f32_16x16x32_bf16 v[88:91], v[218:221], v[178:181], v[88:91]
	v_mfma_f32_16x16x32_bf16 v[84:87], v[210:213], v[186:189], v[84:87]
	v_mfma_f32_16x16x32_bf16 v[80:83], v[218:221], v[186:189], v[80:83]
	v_mfma_f32_16x16x32_bf16 v[76:79], v[210:213], v[194:197], v[76:79]
	v_mfma_f32_16x16x32_bf16 v[72:75], v[218:221], v[194:197], v[72:75]
	v_mfma_f32_16x16x32_bf16 v[68:71], v[210:213], v[202:205], v[68:71]
	v_mfma_f32_16x16x32_bf16 v[64:67], v[218:221], v[202:205], v[64:67]
	s_setprio 0
	s_mov_b32 m0, s52
	v_lshl_add_u64 v[226:227], s[36:37], 0, v[130:131]
	s_barrier
	ds_read_b128 v[166:169], v146 offset:16384
	ds_read_b128 v[178:181], v146 offset:17408
	ds_read_b128 v[182:185], v146 offset:18432
	ds_read_b128 v[186:189], v146 offset:19456
	ds_read_b128 v[190:193], v146 offset:20480
	ds_read_b128 v[194:197], v146 offset:21504
	ds_read_b128 v[198:201], v146 offset:22528
	ds_read_b128 v[202:205], v146 offset:23552
	global_load_lds_dwordx4 v[226:227], off
	v_lshl_add_u64 v[228:229], s[36:37], 0, v[128:129]
	s_mov_b32 m0, s53
	s_nop 0
	global_load_lds_dwordx4 v[228:229], off
	s_barrier
	s_waitcnt lgkmcnt(0)
	s_setprio 1
	s_waitcnt lgkmcnt(0)
	v_mfma_f32_16x16x32_bf16 v[60:63], v[150:153], v[166:169], v[60:63]
	v_mfma_f32_16x16x32_bf16 v[56:59], v[158:161], v[166:169], v[56:59]
	v_mfma_f32_16x16x32_bf16 v[52:55], v[150:153], v[182:185], v[52:55]
	v_mfma_f32_16x16x32_bf16 v[48:51], v[158:161], v[182:185], v[48:51]
	v_mfma_f32_16x16x32_bf16 v[44:47], v[150:153], v[190:193], v[44:47]
	v_mfma_f32_16x16x32_bf16 v[40:43], v[158:161], v[190:193], v[40:43]
	v_mfma_f32_16x16x32_bf16 v[36:39], v[150:153], v[198:201], v[36:39]
	v_mfma_f32_16x16x32_bf16 v[32:35], v[158:161], v[198:201], v[32:35]
	v_mfma_f32_16x16x32_bf16 v[60:63], v[154:157], v[178:181], v[60:63]
	v_mfma_f32_16x16x32_bf16 v[56:59], v[162:165], v[178:181], v[56:59]
	v_mfma_f32_16x16x32_bf16 v[52:55], v[154:157], v[186:189], v[52:55]
	v_mfma_f32_16x16x32_bf16 v[48:51], v[162:165], v[186:189], v[48:51]
	v_mfma_f32_16x16x32_bf16 v[44:47], v[154:157], v[194:197], v[44:47]
	v_mfma_f32_16x16x32_bf16 v[40:43], v[162:165], v[194:197], v[40:43]
	v_mfma_f32_16x16x32_bf16 v[36:39], v[154:157], v[202:205], v[36:39]
	v_mfma_f32_16x16x32_bf16 v[32:35], v[162:165], v[202:205], v[32:35]
	s_setprio 0
	s_barrier
	s_add_u32 s70, s34, 0x40000
	s_addc_u32 s71, s35, 0
	s_add_i32 s33, s64, s51
	v_lshl_add_u64 v[150:151], s[70:71], 0, v[130:131]
	s_mov_b32 m0, s33
	s_nop 0
	global_load_lds_dwordx4 v[150:151], off
	v_lshl_add_u64 v[150:151], s[70:71], 0, v[128:129]
	s_add_i32 m0, s33, 0x2000
	s_nop 0
	global_load_lds_dwordx4 v[150:151], off
	s_waitcnt vmcnt(6)
	s_barrier
	s_setprio 1
	v_mfma_f32_16x16x32_bf16 v[28:31], v[206:209], v[166:169], v[28:31]
	v_mfma_f32_16x16x32_bf16 v[24:27], v[214:217], v[166:169], v[24:27]
	v_mfma_f32_16x16x32_bf16 v[20:23], v[206:209], v[182:185], v[20:23]
	v_mfma_f32_16x16x32_bf16 v[16:19], v[214:217], v[182:185], v[16:19]
	v_mfma_f32_16x16x32_bf16 v[12:15], v[206:209], v[190:193], v[12:15]
	v_mfma_f32_16x16x32_bf16 v[8:11], v[214:217], v[190:193], v[8:11]
	v_mfma_f32_16x16x32_bf16 v[4:7], v[206:209], v[198:201], v[4:7]
	v_mfma_f32_16x16x32_bf16 v[0:3], v[214:217], v[198:201], v[0:3]
	v_mfma_f32_16x16x32_bf16 v[28:31], v[210:213], v[178:181], v[28:31]
	v_mfma_f32_16x16x32_bf16 v[24:27], v[218:221], v[178:181], v[24:27]
	v_mfma_f32_16x16x32_bf16 v[20:23], v[210:213], v[186:189], v[20:23]
	v_mfma_f32_16x16x32_bf16 v[16:19], v[218:221], v[186:189], v[16:19]
	v_mfma_f32_16x16x32_bf16 v[12:15], v[210:213], v[194:197], v[12:15]
	v_mfma_f32_16x16x32_bf16 v[8:11], v[218:221], v[194:197], v[8:11]
	v_mfma_f32_16x16x32_bf16 v[4:7], v[210:213], v[202:205], v[4:7]
	v_mfma_f32_16x16x32_bf16 v[0:3], v[218:221], v[202:205], v[0:3]
	s_setprio 0
	s_add_i32 s33, 0, 0x18000
	v_add_u32_e32 v132, s33, v143
	s_barrier
	ds_read_b128 v[150:153], v132
	ds_read_b128 v[154:157], v132 offset:1024
	ds_read_b128 v[158:161], v132 offset:2048
	ds_read_b128 v[162:165], v132 offset:3072
	s_add_u32 s36, s36, 0x40000
	s_addc_u32 s37, s37, 0
	s_mov_b32 m0, s54
	v_lshl_add_u64 v[206:207], s[36:37], 0, v[130:131]
	ds_read_b128 v[166:169], v146 offset:32768
	ds_read_b128 v[178:181], v146 offset:33792
	ds_read_b128 v[182:185], v146 offset:34816
	ds_read_b128 v[186:189], v146 offset:35840
	ds_read_b128 v[190:193], v146 offset:36864
	ds_read_b128 v[194:197], v146 offset:37888
	ds_read_b128 v[198:201], v146 offset:38912
	ds_read_b128 v[202:205], v146 offset:39936
	global_load_lds_dwordx4 v[206:207], off
	v_lshl_add_u64 v[206:207], s[36:37], 0, v[128:129]
	s_mov_b32 m0, s55
	s_nop 0
	global_load_lds_dwordx4 v[206:207], off
	s_waitcnt lgkmcnt(8)
	s_barrier
	s_waitcnt lgkmcnt(0)
	s_setprio 1
	s_waitcnt lgkmcnt(0)
	v_mfma_f32_16x16x32_bf16 v[124:127], v[150:153], v[166:169], v[124:127]
	v_mfma_f32_16x16x32_bf16 v[120:123], v[158:161], v[166:169], v[120:123]
	v_mfma_f32_16x16x32_bf16 v[116:119], v[150:153], v[182:185], v[116:119]
	v_mfma_f32_16x16x32_bf16 v[112:115], v[158:161], v[182:185], v[112:115]
	v_mfma_f32_16x16x32_bf16 v[108:111], v[150:153], v[190:193], v[108:111]
	v_mfma_f32_16x16x32_bf16 v[104:107], v[158:161], v[190:193], v[104:107]
	v_mfma_f32_16x16x32_bf16 v[100:103], v[150:153], v[198:201], v[100:103]
	v_mfma_f32_16x16x32_bf16 v[96:99], v[158:161], v[198:201], v[96:99]
	v_mfma_f32_16x16x32_bf16 v[124:127], v[154:157], v[178:181], v[124:127]
	v_mfma_f32_16x16x32_bf16 v[120:123], v[162:165], v[178:181], v[120:123]
	v_mfma_f32_16x16x32_bf16 v[116:119], v[154:157], v[186:189], v[116:119]
	v_mfma_f32_16x16x32_bf16 v[112:115], v[162:165], v[186:189], v[112:115]
	v_mfma_f32_16x16x32_bf16 v[108:111], v[154:157], v[194:197], v[108:111]
	v_mfma_f32_16x16x32_bf16 v[104:107], v[162:165], v[194:197], v[104:107]
	v_mfma_f32_16x16x32_bf16 v[100:103], v[154:157], v[202:205], v[100:103]
	v_mfma_f32_16x16x32_bf16 v[96:99], v[162:165], v[202:205], v[96:99]
	s_setprio 0
	s_barrier
	s_add_i32 s36, 0, 0x1c000
	s_add_i32 s33, s33, s51
	v_add_u32_e32 v132, s36, v143
	v_lshl_add_u64 v[222:223], v[222:223], 0, s[12:13]
	s_mov_b32 m0, s33
	ds_read_b128 v[206:209], v132
	ds_read_b128 v[210:213], v132 offset:1024
	ds_read_b128 v[214:217], v132 offset:2048
	ds_read_b128 v[218:221], v132 offset:3072
	global_load_lds_dwordx4 v[222:223], off
	v_lshl_add_u64 v[222:223], v[224:225], 0, s[12:13]
	s_add_i32 m0, s33, 0x2000
	s_nop 0
	global_load_lds_dwordx4 v[222:223], off
	s_barrier
	s_waitcnt lgkmcnt(0)
	s_setprio 1
	s_waitcnt lgkmcnt(0)
	v_mfma_f32_16x16x32_bf16 v[92:95], v[206:209], v[166:169], v[92:95]
	v_mfma_f32_16x16x32_bf16 v[88:91], v[214:217], v[166:169], v[88:91]
	v_mfma_f32_16x16x32_bf16 v[84:87], v[206:209], v[182:185], v[84:87]
	v_mfma_f32_16x16x32_bf16 v[80:83], v[214:217], v[182:185], v[80:83]
	v_mfma_f32_16x16x32_bf16 v[76:79], v[206:209], v[190:193], v[76:79]
	v_mfma_f32_16x16x32_bf16 v[72:75], v[214:217], v[190:193], v[72:75]
	v_mfma_f32_16x16x32_bf16 v[68:71], v[206:209], v[198:201], v[68:71]
	v_mfma_f32_16x16x32_bf16 v[64:67], v[214:217], v[198:201], v[64:67]
	v_mfma_f32_16x16x32_bf16 v[92:95], v[210:213], v[178:181], v[92:95]
	v_mfma_f32_16x16x32_bf16 v[88:91], v[218:221], v[178:181], v[88:91]
	v_mfma_f32_16x16x32_bf16 v[84:87], v[210:213], v[186:189], v[84:87]
	v_mfma_f32_16x16x32_bf16 v[80:83], v[218:221], v[186:189], v[80:83]
	v_mfma_f32_16x16x32_bf16 v[76:79], v[210:213], v[194:197], v[76:79]
	v_mfma_f32_16x16x32_bf16 v[72:75], v[218:221], v[194:197], v[72:75]
	v_mfma_f32_16x16x32_bf16 v[68:71], v[210:213], v[202:205], v[68:71]
	v_mfma_f32_16x16x32_bf16 v[64:67], v[218:221], v[202:205], v[64:67]
	s_setprio 0
	s_mov_b32 m0, s59
	v_lshl_add_u64 v[222:223], v[226:227], 0, s[12:13]
	s_barrier
	ds_read_b128 v[166:169], v146 offset:49152
	ds_read_b128 v[178:181], v146 offset:50176
	ds_read_b128 v[182:185], v146 offset:51200
	ds_read_b128 v[186:189], v146 offset:52224
	ds_read_b128 v[190:193], v146 offset:53248
	ds_read_b128 v[194:197], v146 offset:54272
	ds_read_b128 v[198:201], v146 offset:55296
	ds_read_b128 v[202:205], v146 offset:56320
	global_load_lds_dwordx4 v[222:223], off
	v_lshl_add_u64 v[222:223], v[228:229], 0, s[12:13]
	s_mov_b32 m0, s60
	s_nop 0
	global_load_lds_dwordx4 v[222:223], off
	s_barrier
	s_waitcnt lgkmcnt(0)
	s_setprio 1
	s_waitcnt lgkmcnt(0)
	v_mfma_f32_16x16x32_bf16 v[60:63], v[150:153], v[166:169], v[60:63]
	v_mfma_f32_16x16x32_bf16 v[56:59], v[158:161], v[166:169], v[56:59]
	v_mfma_f32_16x16x32_bf16 v[52:55], v[150:153], v[182:185], v[52:55]
	v_mfma_f32_16x16x32_bf16 v[48:51], v[158:161], v[182:185], v[48:51]
	v_mfma_f32_16x16x32_bf16 v[44:47], v[150:153], v[190:193], v[44:47]
	v_mfma_f32_16x16x32_bf16 v[40:43], v[158:161], v[190:193], v[40:43]
	v_mfma_f32_16x16x32_bf16 v[36:39], v[150:153], v[198:201], v[36:39]
	v_mfma_f32_16x16x32_bf16 v[32:35], v[158:161], v[198:201], v[32:35]
	v_mfma_f32_16x16x32_bf16 v[60:63], v[154:157], v[178:181], v[60:63]
	v_mfma_f32_16x16x32_bf16 v[56:59], v[162:165], v[178:181], v[56:59]
	v_mfma_f32_16x16x32_bf16 v[52:55], v[154:157], v[186:189], v[52:55]
	v_mfma_f32_16x16x32_bf16 v[48:51], v[162:165], v[186:189], v[48:51]
	v_mfma_f32_16x16x32_bf16 v[44:47], v[154:157], v[194:197], v[44:47]
	v_mfma_f32_16x16x32_bf16 v[40:43], v[162:165], v[194:197], v[40:43]
	v_mfma_f32_16x16x32_bf16 v[36:39], v[154:157], v[202:205], v[36:39]
	v_mfma_f32_16x16x32_bf16 v[32:35], v[162:165], v[202:205], v[32:35]
	s_setprio 0
	s_barrier
	s_add_u32 s34, s34, 0x40080
	s_addc_u32 s35, s35, 0
	s_add_i32 s33, s36, s51
	v_lshl_add_u64 v[150:151], s[34:35], 0, v[130:131]
	s_mov_b32 m0, s33
	s_nop 0
	global_load_lds_dwordx4 v[150:151], off
	v_lshl_add_u64 v[150:151], s[34:35], 0, v[128:129]
	s_add_i32 m0, s33, 0x2000
	s_nop 0
	global_load_lds_dwordx4 v[150:151], off
	s_waitcnt vmcnt(6)
	s_barrier
	s_setprio 1
	v_mfma_f32_16x16x32_bf16 v[28:31], v[206:209], v[166:169], v[28:31]
	v_mfma_f32_16x16x32_bf16 v[24:27], v[214:217], v[166:169], v[24:27]
	v_mfma_f32_16x16x32_bf16 v[20:23], v[206:209], v[182:185], v[20:23]
	v_mfma_f32_16x16x32_bf16 v[16:19], v[214:217], v[182:185], v[16:19]
	v_mfma_f32_16x16x32_bf16 v[12:15], v[206:209], v[190:193], v[12:15]
	v_mfma_f32_16x16x32_bf16 v[8:11], v[214:217], v[190:193], v[8:11]
	v_mfma_f32_16x16x32_bf16 v[4:7], v[206:209], v[198:201], v[4:7]
	v_mfma_f32_16x16x32_bf16 v[0:3], v[214:217], v[198:201], v[0:3]
	v_mfma_f32_16x16x32_bf16 v[28:31], v[210:213], v[178:181], v[28:31]
	v_mfma_f32_16x16x32_bf16 v[24:27], v[218:221], v[178:181], v[24:27]
	v_mfma_f32_16x16x32_bf16 v[20:23], v[210:213], v[186:189], v[20:23]
	v_mfma_f32_16x16x32_bf16 v[16:19], v[218:221], v[186:189], v[16:19]
	v_mfma_f32_16x16x32_bf16 v[12:15], v[210:213], v[194:197], v[12:15]
	v_mfma_f32_16x16x32_bf16 v[8:11], v[218:221], v[194:197], v[8:11]
	v_mfma_f32_16x16x32_bf16 v[4:7], v[210:213], v[202:205], v[4:7]
	v_mfma_f32_16x16x32_bf16 v[0:3], v[218:221], v[202:205], v[0:3]
	s_setprio 0
	s_add_i32 s69, s69, 2
	s_add_u32 s67, s67, 0x100
	s_addc_u32 s68, s68, 0
	s_add_u32 s30, s30, 0x100
	s_addc_u32 s31, s31, 0
	s_cmp_gt_u32 s69, 13
	s_barrier
	s_cbranch_scc0 .LBB0_1985
	s_lshl_b32 s21, s28, 21
	s_lshl_b32 s23, s29, 17
	s_add_i32 s21, s21, s23
	s_lshl_b32 s23, s57, 7
	s_add_i32 s21, s21, s23
	s_lshr_b32 s23, s58, 6
	s_lshl_b32 s23, s23, 15
	s_add_i32 s21, s21, s23
	s_bfe_u32 s23, s58, 0x10005
	s_lshl_b32 s23, s23, 6
	s_add_i32 s21, s21, s23
	v_lshl_add_u32 v132, v142, 7, s21
	v_lshl_add_u32 v132, v144, 2, v132
	v_lshrrev_b32_e32 v152, 2, v144
	v_and_b32_e32 v149, 1, v152
	v_lshrrev_b32_e32 v150, 1, v152
	v_lshl_or_b32 v149, v149, 1, v150
	v_xor_b32_e32 v150, 2, v149
	v_lshl_add_u32 v149, v149, 4, v142
	v_lshl_add_u32 v150, v150, 4, v142
	v_lshlrev_b32_e32 v149, 2, v149
	v_lshlrev_b32_e32 v150, 2, v150
	v_and_b32_e32 v151, 4, v144
	v_cmp_ne_u32_e64 s[30:31], 0, v151
	v_cmp_lt_u32_e64 s[34:35], 4, v144
	v_max_f32_e32 v124, v124, v124
	v_max_f32_e32 v125, v125, v125
	v_max_f32_e32 v126, v126, v126
	v_max_f32_e32 v127, v127, v127
	v_max_f32_e32 v124, 0, v124
	v_max_f32_e32 v125, 0, v125
	v_max_f32_e32 v126, 0, v126
	v_max_f32_e32 v127, 0, v127
	v_pk_mul_f32 v[124:125], v[124:125], v[124:125]
	v_pk_mul_f32 v[126:127], v[126:127], v[126:127]
	v_cvt_pk_bf16_f32 v124, v124, v125
	v_cvt_pk_bf16_f32 v125, v126, v127
	v_max_f32_e32 v120, v120, v120
	v_max_f32_e32 v121, v121, v121
	v_max_f32_e32 v122, v122, v122
	v_max_f32_e32 v123, v123, v123
	v_max_f32_e32 v120, 0, v120
	v_max_f32_e32 v121, 0, v121
	v_max_f32_e32 v122, 0, v122
	v_max_f32_e32 v123, 0, v123
	v_pk_mul_f32 v[120:121], v[120:121], v[120:121]
	v_pk_mul_f32 v[122:123], v[122:123], v[122:123]
	v_cvt_pk_bf16_f32 v120, v120, v121
	v_cvt_pk_bf16_f32 v121, v122, v123
	v_cndmask_b32_e64 v126, v124, v120, s[30:31]
	v_cndmask_b32_e64 v127, v125, v121, s[30:31]
	v_cndmask_b32_e64 v122, v120, v124, s[30:31]
	v_cndmask_b32_e64 v123, v121, v125, s[30:31]
	ds_permute_b32 v124, v149, v126
	ds_permute_b32 v125, v149, v127
	ds_permute_b32 v120, v150, v122
	ds_permute_b32 v121, v150, v123
	v_max_f32_e32 v92, v92, v92
	v_max_f32_e32 v93, v93, v93
	v_max_f32_e32 v94, v94, v94
	v_max_f32_e32 v95, v95, v95
	v_max_f32_e32 v92, 0, v92
	v_max_f32_e32 v93, 0, v93
	v_max_f32_e32 v94, 0, v94
	v_max_f32_e32 v95, 0, v95
	v_pk_mul_f32 v[92:93], v[92:93], v[92:93]
	v_pk_mul_f32 v[94:95], v[94:95], v[94:95]
	v_cvt_pk_bf16_f32 v92, v92, v93
	v_cvt_pk_bf16_f32 v93, v94, v95
	v_max_f32_e32 v88, v88, v88
	v_max_f32_e32 v89, v89, v89
	v_max_f32_e32 v90, v90, v90
	v_max_f32_e32 v91, v91, v91
	v_max_f32_e32 v88, 0, v88
	v_max_f32_e32 v89, 0, v89
	v_max_f32_e32 v90, 0, v90
	v_max_f32_e32 v91, 0, v91
	v_pk_mul_f32 v[88:89], v[88:89], v[88:89]
	v_pk_mul_f32 v[90:91], v[90:91], v[90:91]
	v_cvt_pk_bf16_f32 v88, v88, v89
	v_cvt_pk_bf16_f32 v89, v90, v91
	v_cndmask_b32_e64 v94, v92, v88, s[30:31]
	v_cndmask_b32_e64 v95, v93, v89, s[30:31]
	v_cndmask_b32_e64 v90, v88, v92, s[30:31]
	v_cndmask_b32_e64 v91, v89, v93, s[30:31]
	ds_permute_b32 v92, v149, v94
	ds_permute_b32 v93, v149, v95
	ds_permute_b32 v88, v150, v90
	ds_permute_b32 v89, v150, v91
	s_waitcnt lgkmcnt(4)
	v_cndmask_b32_e64 v126, v120, v124, s[34:35]
	v_cndmask_b32_e64 v127, v121, v125, s[34:35]
	v_cndmask_b32_e64 v124, v124, v120, s[34:35]
	v_cndmask_b32_e64 v125, v125, v121, s[34:35]
	global_store_dwordx4 v132, v[124:127], s[14:15]
	v_max_f32_e32 v116, v116, v116
	v_max_f32_e32 v117, v117, v117
	v_max_f32_e32 v118, v118, v118
	v_max_f32_e32 v119, v119, v119
	v_max_f32_e32 v116, 0, v116
	v_max_f32_e32 v117, 0, v117
	v_max_f32_e32 v118, 0, v118
	v_max_f32_e32 v119, 0, v119
	v_pk_mul_f32 v[116:117], v[116:117], v[116:117]
	v_pk_mul_f32 v[118:119], v[118:119], v[118:119]
	v_cvt_pk_bf16_f32 v116, v116, v117
	v_cvt_pk_bf16_f32 v117, v118, v119
	v_max_f32_e32 v112, v112, v112
	v_max_f32_e32 v113, v113, v113
	v_max_f32_e32 v114, v114, v114
	v_max_f32_e32 v115, v115, v115
	v_max_f32_e32 v112, 0, v112
	v_max_f32_e32 v113, 0, v113
	v_max_f32_e32 v114, 0, v114
	v_max_f32_e32 v115, 0, v115
	v_pk_mul_f32 v[112:113], v[112:113], v[112:113]
	v_pk_mul_f32 v[114:115], v[114:115], v[114:115]
	v_cvt_pk_bf16_f32 v112, v112, v113
	v_cvt_pk_bf16_f32 v113, v114, v115
	v_cndmask_b32_e64 v118, v116, v112, s[30:31]
	v_cndmask_b32_e64 v119, v117, v113, s[30:31]
	v_cndmask_b32_e64 v114, v112, v116, s[30:31]
	v_cndmask_b32_e64 v115, v113, v117, s[30:31]
	ds_permute_b32 v116, v149, v118
	ds_permute_b32 v117, v149, v119
	ds_permute_b32 v112, v150, v114
	ds_permute_b32 v113, v150, v115
	s_waitcnt lgkmcnt(4)
	v_cndmask_b32_e64 v94, v88, v92, s[34:35]
	v_cndmask_b32_e64 v95, v89, v93, s[34:35]
	v_cndmask_b32_e64 v92, v92, v88, s[34:35]
	v_cndmask_b32_e64 v93, v93, v89, s[34:35]
	v_add_u32_e32 v151, 0x10000, v132
	global_store_dwordx4 v151, v[92:95], s[14:15]
	v_max_f32_e32 v84, v84, v84
	v_max_f32_e32 v85, v85, v85
	v_max_f32_e32 v86, v86, v86
	v_max_f32_e32 v87, v87, v87
	v_max_f32_e32 v84, 0, v84
	v_max_f32_e32 v85, 0, v85
	v_max_f32_e32 v86, 0, v86
	v_max_f32_e32 v87, 0, v87
	v_pk_mul_f32 v[84:85], v[84:85], v[84:85]
	v_pk_mul_f32 v[86:87], v[86:87], v[86:87]
	v_cvt_pk_bf16_f32 v84, v84, v85
	v_cvt_pk_bf16_f32 v85, v86, v87
	v_max_f32_e32 v80, v80, v80
	v_max_f32_e32 v81, v81, v81
	v_max_f32_e32 v82, v82, v82
	v_max_f32_e32 v83, v83, v83
	v_max_f32_e32 v80, 0, v80
	v_max_f32_e32 v81, 0, v81
	v_max_f32_e32 v82, 0, v82
	v_max_f32_e32 v83, 0, v83
	v_pk_mul_f32 v[80:81], v[80:81], v[80:81]
	v_pk_mul_f32 v[82:83], v[82:83], v[82:83]
	v_cvt_pk_bf16_f32 v80, v80, v81
	v_cvt_pk_bf16_f32 v81, v82, v83
	v_cndmask_b32_e64 v86, v84, v80, s[30:31]
	v_cndmask_b32_e64 v87, v85, v81, s[30:31]
	v_cndmask_b32_e64 v82, v80, v84, s[30:31]
	v_cndmask_b32_e64 v83, v81, v85, s[30:31]
	ds_permute_b32 v84, v149, v86
	ds_permute_b32 v85, v149, v87
	ds_permute_b32 v80, v150, v82
	ds_permute_b32 v81, v150, v83
	s_waitcnt lgkmcnt(4)
	v_cndmask_b32_e64 v118, v112, v116, s[34:35]
	v_cndmask_b32_e64 v119, v113, v117, s[34:35]
	v_cndmask_b32_e64 v116, v116, v112, s[34:35]
	v_cndmask_b32_e64 v117, v117, v113, s[34:35]
	v_add_u32_e32 v151, 0x800, v132
	global_store_dwordx4 v151, v[116:119], s[14:15]
	v_max_f32_e32 v108, v108, v108
	v_max_f32_e32 v109, v109, v109
	v_max_f32_e32 v110, v110, v110
	v_max_f32_e32 v111, v111, v111
	v_max_f32_e32 v108, 0, v108
	v_max_f32_e32 v109, 0, v109
	v_max_f32_e32 v110, 0, v110
	v_max_f32_e32 v111, 0, v111
	v_pk_mul_f32 v[108:109], v[108:109], v[108:109]
	v_pk_mul_f32 v[110:111], v[110:111], v[110:111]
	v_cvt_pk_bf16_f32 v108, v108, v109
	v_cvt_pk_bf16_f32 v109, v110, v111
	v_max_f32_e32 v104, v104, v104
	v_max_f32_e32 v105, v105, v105
	v_max_f32_e32 v106, v106, v106
	v_max_f32_e32 v107, v107, v107
	v_max_f32_e32 v104, 0, v104
	v_max_f32_e32 v105, 0, v105
	v_max_f32_e32 v106, 0, v106
	v_max_f32_e32 v107, 0, v107
	v_pk_mul_f32 v[104:105], v[104:105], v[104:105]
	v_pk_mul_f32 v[106:107], v[106:107], v[106:107]
	v_cvt_pk_bf16_f32 v104, v104, v105
	v_cvt_pk_bf16_f32 v105, v106, v107
	v_cndmask_b32_e64 v110, v108, v104, s[30:31]
	v_cndmask_b32_e64 v111, v109, v105, s[30:31]
	v_cndmask_b32_e64 v106, v104, v108, s[30:31]
	v_cndmask_b32_e64 v107, v105, v109, s[30:31]
	ds_permute_b32 v108, v149, v110
	ds_permute_b32 v109, v149, v111
	ds_permute_b32 v104, v150, v106
	ds_permute_b32 v105, v150, v107
	s_waitcnt lgkmcnt(4)
	v_cndmask_b32_e64 v86, v80, v84, s[34:35]
	v_cndmask_b32_e64 v87, v81, v85, s[34:35]
	v_cndmask_b32_e64 v84, v84, v80, s[34:35]
	v_cndmask_b32_e64 v85, v85, v81, s[34:35]
	v_add_u32_e32 v151, 0x10800, v132
	global_store_dwordx4 v151, v[84:87], s[14:15]
	v_max_f32_e32 v76, v76, v76
	v_max_f32_e32 v77, v77, v77
	v_max_f32_e32 v78, v78, v78
	v_max_f32_e32 v79, v79, v79
	v_max_f32_e32 v76, 0, v76
	v_max_f32_e32 v77, 0, v77
	v_max_f32_e32 v78, 0, v78
	v_max_f32_e32 v79, 0, v79
	v_pk_mul_f32 v[76:77], v[76:77], v[76:77]
	v_pk_mul_f32 v[78:79], v[78:79], v[78:79]
	v_cvt_pk_bf16_f32 v76, v76, v77
	v_cvt_pk_bf16_f32 v77, v78, v79
	v_max_f32_e32 v72, v72, v72
	v_max_f32_e32 v73, v73, v73
	v_max_f32_e32 v74, v74, v74
	v_max_f32_e32 v75, v75, v75
	v_max_f32_e32 v72, 0, v72
	v_max_f32_e32 v73, 0, v73
	v_max_f32_e32 v74, 0, v74
	v_max_f32_e32 v75, 0, v75
	v_pk_mul_f32 v[72:73], v[72:73], v[72:73]
	v_pk_mul_f32 v[74:75], v[74:75], v[74:75]
	v_cvt_pk_bf16_f32 v72, v72, v73
	v_cvt_pk_bf16_f32 v73, v74, v75
	v_cndmask_b32_e64 v78, v76, v72, s[30:31]
	v_cndmask_b32_e64 v79, v77, v73, s[30:31]
	v_cndmask_b32_e64 v74, v72, v76, s[30:31]
	v_cndmask_b32_e64 v75, v73, v77, s[30:31]
	ds_permute_b32 v76, v149, v78
	ds_permute_b32 v77, v149, v79
	ds_permute_b32 v72, v150, v74
	ds_permute_b32 v73, v150, v75
	s_waitcnt lgkmcnt(4)
	v_cndmask_b32_e64 v110, v104, v108, s[34:35]
	v_cndmask_b32_e64 v111, v105, v109, s[34:35]
	v_cndmask_b32_e64 v108, v108, v104, s[34:35]
	v_cndmask_b32_e64 v109, v109, v105, s[34:35]
	v_add_u32_e32 v151, 0x1000, v132
	global_store_dwordx4 v151, v[108:111], s[14:15]
	v_max_f32_e32 v100, v100, v100
	v_max_f32_e32 v101, v101, v101
	v_max_f32_e32 v102, v102, v102
	v_max_f32_e32 v103, v103, v103
	v_max_f32_e32 v100, 0, v100
	v_max_f32_e32 v101, 0, v101
	v_max_f32_e32 v102, 0, v102
	v_max_f32_e32 v103, 0, v103
	v_pk_mul_f32 v[100:101], v[100:101], v[100:101]
	v_pk_mul_f32 v[102:103], v[102:103], v[102:103]
	v_cvt_pk_bf16_f32 v100, v100, v101
	v_cvt_pk_bf16_f32 v101, v102, v103
	v_max_f32_e32 v96, v96, v96
	v_max_f32_e32 v97, v97, v97
	v_max_f32_e32 v98, v98, v98
	v_max_f32_e32 v99, v99, v99
	v_max_f32_e32 v96, 0, v96
	v_max_f32_e32 v97, 0, v97
	v_max_f32_e32 v98, 0, v98
	v_max_f32_e32 v99, 0, v99
	v_pk_mul_f32 v[96:97], v[96:97], v[96:97]
	v_pk_mul_f32 v[98:99], v[98:99], v[98:99]
	v_cvt_pk_bf16_f32 v96, v96, v97
	v_cvt_pk_bf16_f32 v97, v98, v99
	v_cndmask_b32_e64 v102, v100, v96, s[30:31]
	v_cndmask_b32_e64 v103, v101, v97, s[30:31]
	v_cndmask_b32_e64 v98, v96, v100, s[30:31]
	v_cndmask_b32_e64 v99, v97, v101, s[30:31]
	ds_permute_b32 v100, v149, v102
	ds_permute_b32 v101, v149, v103
	ds_permute_b32 v96, v150, v98
	ds_permute_b32 v97, v150, v99
	s_waitcnt lgkmcnt(4)
	v_cndmask_b32_e64 v78, v72, v76, s[34:35]
	v_cndmask_b32_e64 v79, v73, v77, s[34:35]
	v_cndmask_b32_e64 v76, v76, v72, s[34:35]
	v_cndmask_b32_e64 v77, v77, v73, s[34:35]
	v_add_u32_e32 v151, 0x11000, v132
	global_store_dwordx4 v151, v[76:79], s[14:15]
	v_max_f32_e32 v68, v68, v68
	v_max_f32_e32 v69, v69, v69
	v_max_f32_e32 v70, v70, v70
	v_max_f32_e32 v71, v71, v71
	v_max_f32_e32 v68, 0, v68
	v_max_f32_e32 v69, 0, v69
	v_max_f32_e32 v70, 0, v70
	v_max_f32_e32 v71, 0, v71
	v_pk_mul_f32 v[68:69], v[68:69], v[68:69]
	v_pk_mul_f32 v[70:71], v[70:71], v[70:71]
	v_cvt_pk_bf16_f32 v68, v68, v69
	v_cvt_pk_bf16_f32 v69, v70, v71
	v_max_f32_e32 v64, v64, v64
	v_max_f32_e32 v65, v65, v65
	v_max_f32_e32 v66, v66, v66
	v_max_f32_e32 v67, v67, v67
	v_max_f32_e32 v64, 0, v64
	v_max_f32_e32 v65, 0, v65
	v_max_f32_e32 v66, 0, v66
	v_max_f32_e32 v67, 0, v67
	v_pk_mul_f32 v[64:65], v[64:65], v[64:65]
	v_pk_mul_f32 v[66:67], v[66:67], v[66:67]
	v_cvt_pk_bf16_f32 v64, v64, v65
	v_cvt_pk_bf16_f32 v65, v66, v67
	v_cndmask_b32_e64 v70, v68, v64, s[30:31]
	v_cndmask_b32_e64 v71, v69, v65, s[30:31]
	v_cndmask_b32_e64 v66, v64, v68, s[30:31]
	v_cndmask_b32_e64 v67, v65, v69, s[30:31]
	ds_permute_b32 v68, v149, v70
	ds_permute_b32 v69, v149, v71
	ds_permute_b32 v64, v150, v66
	ds_permute_b32 v65, v150, v67
	s_waitcnt lgkmcnt(4)
	v_cndmask_b32_e64 v102, v96, v100, s[34:35]
	v_cndmask_b32_e64 v103, v97, v101, s[34:35]
	v_cndmask_b32_e64 v100, v100, v96, s[34:35]
	v_cndmask_b32_e64 v101, v101, v97, s[34:35]
	v_add_u32_e32 v151, 0x1800, v132
	global_store_dwordx4 v151, v[100:103], s[14:15]
	v_max_f32_e32 v60, v60, v60
	v_max_f32_e32 v61, v61, v61
	v_max_f32_e32 v62, v62, v62
	v_max_f32_e32 v63, v63, v63
	v_max_f32_e32 v60, 0, v60
	v_max_f32_e32 v61, 0, v61
	v_max_f32_e32 v62, 0, v62
	v_max_f32_e32 v63, 0, v63
	v_pk_mul_f32 v[60:61], v[60:61], v[60:61]
	v_pk_mul_f32 v[62:63], v[62:63], v[62:63]
	v_cvt_pk_bf16_f32 v60, v60, v61
	v_cvt_pk_bf16_f32 v61, v62, v63
	v_max_f32_e32 v56, v56, v56
	v_max_f32_e32 v57, v57, v57
	v_max_f32_e32 v58, v58, v58
	v_max_f32_e32 v59, v59, v59
	v_max_f32_e32 v56, 0, v56
	v_max_f32_e32 v57, 0, v57
	v_max_f32_e32 v58, 0, v58
	v_max_f32_e32 v59, 0, v59
	v_pk_mul_f32 v[56:57], v[56:57], v[56:57]
	v_pk_mul_f32 v[58:59], v[58:59], v[58:59]
	v_cvt_pk_bf16_f32 v56, v56, v57
	v_cvt_pk_bf16_f32 v57, v58, v59
	v_cndmask_b32_e64 v62, v60, v56, s[30:31]
	v_cndmask_b32_e64 v63, v61, v57, s[30:31]
	v_cndmask_b32_e64 v58, v56, v60, s[30:31]
	v_cndmask_b32_e64 v59, v57, v61, s[30:31]
	ds_permute_b32 v60, v149, v62
	ds_permute_b32 v61, v149, v63
	ds_permute_b32 v56, v150, v58
	ds_permute_b32 v57, v150, v59
	s_waitcnt lgkmcnt(4)
	v_cndmask_b32_e64 v70, v64, v68, s[34:35]
	v_cndmask_b32_e64 v71, v65, v69, s[34:35]
	v_cndmask_b32_e64 v68, v68, v64, s[34:35]
	v_cndmask_b32_e64 v69, v69, v65, s[34:35]
	v_add_u32_e32 v151, 0x11800, v132
	global_store_dwordx4 v151, v[68:71], s[14:15]
	v_max_f32_e32 v28, v28, v28
	v_max_f32_e32 v29, v29, v29
	v_max_f32_e32 v30, v30, v30
	v_max_f32_e32 v31, v31, v31
	v_max_f32_e32 v28, 0, v28
	v_max_f32_e32 v29, 0, v29
	v_max_f32_e32 v30, 0, v30
	v_max_f32_e32 v31, 0, v31
	v_pk_mul_f32 v[28:29], v[28:29], v[28:29]
	v_pk_mul_f32 v[30:31], v[30:31], v[30:31]
	v_cvt_pk_bf16_f32 v28, v28, v29
	v_cvt_pk_bf16_f32 v29, v30, v31
	v_max_f32_e32 v24, v24, v24
	v_max_f32_e32 v25, v25, v25
	v_max_f32_e32 v26, v26, v26
	v_max_f32_e32 v27, v27, v27
	v_max_f32_e32 v24, 0, v24
	v_max_f32_e32 v25, 0, v25
	v_max_f32_e32 v26, 0, v26
	v_max_f32_e32 v27, 0, v27
	v_pk_mul_f32 v[24:25], v[24:25], v[24:25]
	v_pk_mul_f32 v[26:27], v[26:27], v[26:27]
	v_cvt_pk_bf16_f32 v24, v24, v25
	v_cvt_pk_bf16_f32 v25, v26, v27
	v_cndmask_b32_e64 v30, v28, v24, s[30:31]
	v_cndmask_b32_e64 v31, v29, v25, s[30:31]
	v_cndmask_b32_e64 v26, v24, v28, s[30:31]
	v_cndmask_b32_e64 v27, v25, v29, s[30:31]
	ds_permute_b32 v28, v149, v30
	ds_permute_b32 v29, v149, v31
	ds_permute_b32 v24, v150, v26
	ds_permute_b32 v25, v150, v27
	s_waitcnt lgkmcnt(4)
	v_cndmask_b32_e64 v62, v56, v60, s[34:35]
	v_cndmask_b32_e64 v63, v57, v61, s[34:35]
	v_cndmask_b32_e64 v60, v60, v56, s[34:35]
	v_cndmask_b32_e64 v61, v61, v57, s[34:35]
	v_add_u32_e32 v151, 0x4000, v132
	global_store_dwordx4 v151, v[60:63], s[14:15]
	v_max_f32_e32 v52, v52, v52
	v_max_f32_e32 v53, v53, v53
	v_max_f32_e32 v54, v54, v54
	v_max_f32_e32 v55, v55, v55
	v_max_f32_e32 v52, 0, v52
	v_max_f32_e32 v53, 0, v53
	v_max_f32_e32 v54, 0, v54
	v_max_f32_e32 v55, 0, v55
	v_pk_mul_f32 v[52:53], v[52:53], v[52:53]
	v_pk_mul_f32 v[54:55], v[54:55], v[54:55]
	v_cvt_pk_bf16_f32 v52, v52, v53
	v_cvt_pk_bf16_f32 v53, v54, v55
	v_max_f32_e32 v48, v48, v48
	v_max_f32_e32 v49, v49, v49
	v_max_f32_e32 v50, v50, v50
	v_max_f32_e32 v51, v51, v51
	v_max_f32_e32 v48, 0, v48
	v_max_f32_e32 v49, 0, v49
	v_max_f32_e32 v50, 0, v50
	v_max_f32_e32 v51, 0, v51
	v_pk_mul_f32 v[48:49], v[48:49], v[48:49]
	v_pk_mul_f32 v[50:51], v[50:51], v[50:51]
	v_cvt_pk_bf16_f32 v48, v48, v49
	v_cvt_pk_bf16_f32 v49, v50, v51
	v_cndmask_b32_e64 v54, v52, v48, s[30:31]
	v_cndmask_b32_e64 v55, v53, v49, s[30:31]
	v_cndmask_b32_e64 v50, v48, v52, s[30:31]
	v_cndmask_b32_e64 v51, v49, v53, s[30:31]
	ds_permute_b32 v52, v149, v54
	ds_permute_b32 v53, v149, v55
	ds_permute_b32 v48, v150, v50
	ds_permute_b32 v49, v150, v51
	s_waitcnt lgkmcnt(4)
	v_cndmask_b32_e64 v30, v24, v28, s[34:35]
	v_cndmask_b32_e64 v31, v25, v29, s[34:35]
	v_cndmask_b32_e64 v28, v28, v24, s[34:35]
	v_cndmask_b32_e64 v29, v29, v25, s[34:35]
	v_add_u32_e32 v151, 0x14000, v132
	global_store_dwordx4 v151, v[28:31], s[14:15]
	v_max_f32_e32 v20, v20, v20
	v_max_f32_e32 v21, v21, v21
	v_max_f32_e32 v22, v22, v22
	v_max_f32_e32 v23, v23, v23
	v_max_f32_e32 v20, 0, v20
	v_max_f32_e32 v21, 0, v21
	v_max_f32_e32 v22, 0, v22
	v_max_f32_e32 v23, 0, v23
	v_pk_mul_f32 v[20:21], v[20:21], v[20:21]
	v_pk_mul_f32 v[22:23], v[22:23], v[22:23]
	v_cvt_pk_bf16_f32 v20, v20, v21
	v_cvt_pk_bf16_f32 v21, v22, v23
	v_max_f32_e32 v16, v16, v16
	v_max_f32_e32 v17, v17, v17
	v_max_f32_e32 v18, v18, v18
	v_max_f32_e32 v19, v19, v19
	v_max_f32_e32 v16, 0, v16
	v_max_f32_e32 v17, 0, v17
	v_max_f32_e32 v18, 0, v18
	v_max_f32_e32 v19, 0, v19
	v_pk_mul_f32 v[16:17], v[16:17], v[16:17]
	v_pk_mul_f32 v[18:19], v[18:19], v[18:19]
	v_cvt_pk_bf16_f32 v16, v16, v17
	v_cvt_pk_bf16_f32 v17, v18, v19
	v_cndmask_b32_e64 v22, v20, v16, s[30:31]
	v_cndmask_b32_e64 v23, v21, v17, s[30:31]
	v_cndmask_b32_e64 v18, v16, v20, s[30:31]
	v_cndmask_b32_e64 v19, v17, v21, s[30:31]
	ds_permute_b32 v20, v149, v22
	ds_permute_b32 v21, v149, v23
	ds_permute_b32 v16, v150, v18
	ds_permute_b32 v17, v150, v19
	s_waitcnt lgkmcnt(4)
	v_cndmask_b32_e64 v54, v48, v52, s[34:35]
	v_cndmask_b32_e64 v55, v49, v53, s[34:35]
	v_cndmask_b32_e64 v52, v52, v48, s[34:35]
	v_cndmask_b32_e64 v53, v53, v49, s[34:35]
	v_add_u32_e32 v151, 0x4800, v132
	global_store_dwordx4 v151, v[52:55], s[14:15]
	v_max_f32_e32 v44, v44, v44
	v_max_f32_e32 v45, v45, v45
	v_max_f32_e32 v46, v46, v46
	v_max_f32_e32 v47, v47, v47
	v_max_f32_e32 v44, 0, v44
	v_max_f32_e32 v45, 0, v45
	v_max_f32_e32 v46, 0, v46
	v_max_f32_e32 v47, 0, v47
	v_pk_mul_f32 v[44:45], v[44:45], v[44:45]
	v_pk_mul_f32 v[46:47], v[46:47], v[46:47]
	v_cvt_pk_bf16_f32 v44, v44, v45
	v_cvt_pk_bf16_f32 v45, v46, v47
	v_max_f32_e32 v40, v40, v40
	v_max_f32_e32 v41, v41, v41
	v_max_f32_e32 v42, v42, v42
	v_max_f32_e32 v43, v43, v43
	v_max_f32_e32 v40, 0, v40
	v_max_f32_e32 v41, 0, v41
	v_max_f32_e32 v42, 0, v42
	v_max_f32_e32 v43, 0, v43
	v_pk_mul_f32 v[40:41], v[40:41], v[40:41]
	v_pk_mul_f32 v[42:43], v[42:43], v[42:43]
	v_cvt_pk_bf16_f32 v40, v40, v41
	v_cvt_pk_bf16_f32 v41, v42, v43
	v_cndmask_b32_e64 v46, v44, v40, s[30:31]
	v_cndmask_b32_e64 v47, v45, v41, s[30:31]
	v_cndmask_b32_e64 v42, v40, v44, s[30:31]
	v_cndmask_b32_e64 v43, v41, v45, s[30:31]
	ds_permute_b32 v44, v149, v46
	ds_permute_b32 v45, v149, v47
	ds_permute_b32 v40, v150, v42
	ds_permute_b32 v41, v150, v43
	s_waitcnt lgkmcnt(4)
	v_cndmask_b32_e64 v22, v16, v20, s[34:35]
	v_cndmask_b32_e64 v23, v17, v21, s[34:35]
	v_cndmask_b32_e64 v20, v20, v16, s[34:35]
	v_cndmask_b32_e64 v21, v21, v17, s[34:35]
	v_add_u32_e32 v151, 0x14800, v132
	global_store_dwordx4 v151, v[20:23], s[14:15]
	v_max_f32_e32 v12, v12, v12
	v_max_f32_e32 v13, v13, v13
	v_max_f32_e32 v14, v14, v14
	v_max_f32_e32 v15, v15, v15
	v_max_f32_e32 v12, 0, v12
	v_max_f32_e32 v13, 0, v13
	v_max_f32_e32 v14, 0, v14
	v_max_f32_e32 v15, 0, v15
	v_pk_mul_f32 v[12:13], v[12:13], v[12:13]
	v_pk_mul_f32 v[14:15], v[14:15], v[14:15]
	v_cvt_pk_bf16_f32 v12, v12, v13
	v_cvt_pk_bf16_f32 v13, v14, v15
	v_max_f32_e32 v8, v8, v8
	v_max_f32_e32 v9, v9, v9
	v_max_f32_e32 v10, v10, v10
	v_max_f32_e32 v11, v11, v11
	v_max_f32_e32 v8, 0, v8
	v_max_f32_e32 v9, 0, v9
	v_max_f32_e32 v10, 0, v10
	v_max_f32_e32 v11, 0, v11
	v_pk_mul_f32 v[8:9], v[8:9], v[8:9]
	v_pk_mul_f32 v[10:11], v[10:11], v[10:11]
	v_cvt_pk_bf16_f32 v8, v8, v9
	v_cvt_pk_bf16_f32 v9, v10, v11
	v_cndmask_b32_e64 v14, v12, v8, s[30:31]
	v_cndmask_b32_e64 v15, v13, v9, s[30:31]
	v_cndmask_b32_e64 v10, v8, v12, s[30:31]
	v_cndmask_b32_e64 v11, v9, v13, s[30:31]
	ds_permute_b32 v12, v149, v14
	ds_permute_b32 v13, v149, v15
	ds_permute_b32 v8, v150, v10
	ds_permute_b32 v9, v150, v11
	s_waitcnt lgkmcnt(4)
	v_cndmask_b32_e64 v46, v40, v44, s[34:35]
	v_cndmask_b32_e64 v47, v41, v45, s[34:35]
	v_cndmask_b32_e64 v44, v44, v40, s[34:35]
	v_cndmask_b32_e64 v45, v45, v41, s[34:35]
	v_add_u32_e32 v151, 0x5000, v132
	global_store_dwordx4 v151, v[44:47], s[14:15]
	v_max_f32_e32 v36, v36, v36
	v_max_f32_e32 v37, v37, v37
	v_max_f32_e32 v38, v38, v38
	v_max_f32_e32 v39, v39, v39
	v_max_f32_e32 v36, 0, v36
	v_max_f32_e32 v37, 0, v37
	v_max_f32_e32 v38, 0, v38
	v_max_f32_e32 v39, 0, v39
	v_pk_mul_f32 v[36:37], v[36:37], v[36:37]
	v_pk_mul_f32 v[38:39], v[38:39], v[38:39]
	v_cvt_pk_bf16_f32 v36, v36, v37
	v_cvt_pk_bf16_f32 v37, v38, v39
	v_max_f32_e32 v32, v32, v32
	v_max_f32_e32 v33, v33, v33
	v_max_f32_e32 v34, v34, v34
	v_max_f32_e32 v35, v35, v35
	v_max_f32_e32 v32, 0, v32
	v_max_f32_e32 v33, 0, v33
	v_max_f32_e32 v34, 0, v34
	v_max_f32_e32 v35, 0, v35
	v_pk_mul_f32 v[32:33], v[32:33], v[32:33]
	v_pk_mul_f32 v[34:35], v[34:35], v[34:35]
	v_cvt_pk_bf16_f32 v32, v32, v33
	v_cvt_pk_bf16_f32 v33, v34, v35
	v_cndmask_b32_e64 v38, v36, v32, s[30:31]
	v_cndmask_b32_e64 v39, v37, v33, s[30:31]
	v_cndmask_b32_e64 v34, v32, v36, s[30:31]
	v_cndmask_b32_e64 v35, v33, v37, s[30:31]
	ds_permute_b32 v36, v149, v38
	ds_permute_b32 v37, v149, v39
	ds_permute_b32 v32, v150, v34
	ds_permute_b32 v33, v150, v35
	s_waitcnt lgkmcnt(4)
	v_cndmask_b32_e64 v14, v8, v12, s[34:35]
	v_cndmask_b32_e64 v15, v9, v13, s[34:35]
	v_cndmask_b32_e64 v12, v12, v8, s[34:35]
	v_cndmask_b32_e64 v13, v13, v9, s[34:35]
	v_add_u32_e32 v151, 0x15000, v132
	global_store_dwordx4 v151, v[12:15], s[14:15]
	v_max_f32_e32 v4, v4, v4
	v_max_f32_e32 v5, v5, v5
	v_max_f32_e32 v6, v6, v6
	v_max_f32_e32 v7, v7, v7
	v_max_f32_e32 v4, 0, v4
	v_max_f32_e32 v5, 0, v5
	v_max_f32_e32 v6, 0, v6
	v_max_f32_e32 v7, 0, v7
	v_pk_mul_f32 v[4:5], v[4:5], v[4:5]
	v_pk_mul_f32 v[6:7], v[6:7], v[6:7]
	v_cvt_pk_bf16_f32 v4, v4, v5
	v_cvt_pk_bf16_f32 v5, v6, v7
	v_max_f32_e32 v0, v0, v0
	v_max_f32_e32 v1, v1, v1
	v_max_f32_e32 v2, v2, v2
	v_max_f32_e32 v3, v3, v3
	v_max_f32_e32 v0, 0, v0
	v_max_f32_e32 v1, 0, v1
	v_max_f32_e32 v2, 0, v2
	v_max_f32_e32 v3, 0, v3
	v_pk_mul_f32 v[0:1], v[0:1], v[0:1]
	v_pk_mul_f32 v[2:3], v[2:3], v[2:3]
	v_cvt_pk_bf16_f32 v0, v0, v1
	v_cvt_pk_bf16_f32 v1, v2, v3
	v_cndmask_b32_e64 v6, v4, v0, s[30:31]
	v_cndmask_b32_e64 v7, v5, v1, s[30:31]
	v_cndmask_b32_e64 v2, v0, v4, s[30:31]
	v_cndmask_b32_e64 v3, v1, v5, s[30:31]
	ds_permute_b32 v4, v149, v6
	ds_permute_b32 v5, v149, v7
	ds_permute_b32 v0, v150, v2
	ds_permute_b32 v1, v150, v3
	s_waitcnt lgkmcnt(4)
	v_cndmask_b32_e64 v38, v32, v36, s[34:35]
	v_cndmask_b32_e64 v39, v33, v37, s[34:35]
	v_cndmask_b32_e64 v36, v36, v32, s[34:35]
	v_cndmask_b32_e64 v37, v37, v33, s[34:35]
	v_add_u32_e32 v151, 0x5800, v132
	global_store_dwordx4 v151, v[36:39], s[14:15]
	s_waitcnt lgkmcnt(0)
	v_cndmask_b32_e64 v6, v0, v4, s[34:35]
	v_cndmask_b32_e64 v7, v1, v5, s[34:35]
	v_cndmask_b32_e64 v4, v4, v0, s[34:35]
	v_cndmask_b32_e64 v5, v5, v1, s[34:35]
	v_add_u32_e32 v151, 0x15800, v132
	global_store_dwordx4 v151, v[4:7], s[14:15]
	s_and_b64 vcc, exec, s[8:9]
	s_mov_b32 s29, s20
	s_mov_b32 s28, s22
	s_mov_b64 s[30:31], s[26:27]
	s_mov_b64 s[34:35], s[24:25]
	s_cbranch_vccz .LBB0_1982
	s_waitcnt vmcnt(0)
	s_cmpk_gt_u32 s40, 0xff
	s_cbranch_scc1 .LBB0_1989
	s_barrier
